# K-loops: leading half (wr==0) defers its vmcnt(8) from the pre-MMA to the post-MMA barrier
# baseline (speedup 1.0000x reference)
; #define PG8_BAR __builtin_amdgcn_s_barrier()
; template <class Epi>
; __device__ __forceinline__ void gemm_phase(LAS unsigned char* lds, const Gemm g, const StaticOrder& S, const Epi& E) {
;     ...
;         const bool has_next = S.next(ui + 1, nxt);
;         const char* nA = has_next ? (const char*)g.A + (size_t)nxt.pm * tstepA : cA; const char* nB = has_next ? (const char*)g.Bt + (size_t)nxt.pn * tstepB : cB;
;         PG8_KLOOP(cA, cB, nA, nB)
;         if (wr == 0) PG8_BAR;
;         E(acc, cur, wr, wc, fr, fq);
;         if (!has_next) break;
; #pragma unroll
;         for (int a = 0; a < 2; ++a)
; #pragma unroll
;             for (int b = 0; b < 2; ++b)
; #pragma unroll
;                 for (int m = 0; m < 4; ++m)
; #pragma unroll
;                     for (int n = 0; n < 2; ++n) acc[a][b][m][n] = (f32x4){0.f, 0.f, 0.f, 0.f};
.LBB0_136:
	s_ashr_i32 s95, s94, 31
	s_lshl_b64 s[34:35], s[94:95], 20
	s_add_u32 s96, s38, s34
	s_addc_u32 s97, s39, s35
	s_and_b64 s[34:35], s[0:1], exec
	s_cselect_b32 s7, s97, s5
	s_cselect_b32 s9, s96, s4
	s_ashr_i32 s93, s92, 31
	s_lshl_b64 s[34:35], s[92:93], 20
	s_add_u32 s74, s82, s34
	s_addc_u32 s75, s83, s35
	s_and_b64 s[34:35], s[0:1], exec
	s_cselect_b32 s36, s75, s11
	s_cselect_b32 s73, s74, s10
	s_add_u32 s4, s4, 0x80080
	s_addc_u32 s5, s5, 0
	s_add_u32 s76, s10, 0x100
	v_mov_b32_e32 v0, 0
	s_addc_u32 s77, s11, 0
	s_mov_b32 s78, -2
	v_mov_b32_e32 v1, v0
	v_mov_b32_e32 v2, v0
	v_mov_b32_e32 v3, v0
	v_mov_b32_e32 v4, v0
	v_mov_b32_e32 v5, v0
	v_mov_b32_e32 v6, v0
	v_mov_b32_e32 v7, v0
	v_mov_b32_e32 v16, v0
	v_mov_b32_e32 v17, v0
	v_mov_b32_e32 v18, v0
	v_mov_b32_e32 v19, v0
	v_mov_b32_e32 v20, v0
	v_mov_b32_e32 v21, v0
	v_mov_b32_e32 v22, v0
	v_mov_b32_e32 v23, v0
	v_mov_b32_e32 v32, v0
	v_mov_b32_e32 v33, v0
	v_mov_b32_e32 v34, v0
	v_mov_b32_e32 v35, v0
	v_mov_b32_e32 v36, v0
	v_mov_b32_e32 v37, v0
	v_mov_b32_e32 v38, v0
	v_mov_b32_e32 v39, v0
	v_mov_b32_e32 v48, v0
	v_mov_b32_e32 v49, v0
	v_mov_b32_e32 v50, v0
	v_mov_b32_e32 v51, v0
	v_mov_b32_e32 v52, v0
	v_mov_b32_e32 v53, v0
	v_mov_b32_e32 v54, v0
	v_mov_b32_e32 v55, v0
	v_mov_b32_e32 v8, v0
	v_mov_b32_e32 v9, v0
	v_mov_b32_e32 v10, v0
	v_mov_b32_e32 v11, v0
	v_mov_b32_e32 v12, v0
	v_mov_b32_e32 v13, v0
	v_mov_b32_e32 v14, v0
	v_mov_b32_e32 v15, v0
	v_mov_b32_e32 v24, v0
	v_mov_b32_e32 v25, v0
	v_mov_b32_e32 v26, v0
	v_mov_b32_e32 v27, v0
	v_mov_b32_e32 v28, v0
	v_mov_b32_e32 v29, v0
	v_mov_b32_e32 v30, v0
	v_mov_b32_e32 v31, v0
	v_mov_b32_e32 v40, v0
	v_mov_b32_e32 v41, v0
	v_mov_b32_e32 v42, v0
	v_mov_b32_e32 v43, v0
	v_mov_b32_e32 v44, v0
	v_mov_b32_e32 v45, v0
	v_mov_b32_e32 v46, v0
	v_mov_b32_e32 v47, v0
	v_mov_b32_e32 v56, v0
	v_mov_b32_e32 v57, v0
	v_mov_b32_e32 v58, v0
	v_mov_b32_e32 v59, v0
	v_mov_b32_e32 v60, v0
	v_mov_b32_e32 v61, v0
	v_mov_b32_e32 v62, v0
	v_mov_b32_e32 v63, v0
	v_mov_b32_e32 v64, v0
	v_mov_b32_e32 v65, v0
	v_mov_b32_e32 v66, v0
	v_mov_b32_e32 v67, v0
	v_mov_b32_e32 v68, v0
	v_mov_b32_e32 v69, v0
	v_mov_b32_e32 v70, v0
	v_mov_b32_e32 v71, v0
	v_mov_b32_e32 v80, v0
	v_mov_b32_e32 v81, v0
	v_mov_b32_e32 v82, v0
	v_mov_b32_e32 v83, v0
	v_mov_b32_e32 v84, v0
	v_mov_b32_e32 v85, v0
	v_mov_b32_e32 v86, v0
	v_mov_b32_e32 v87, v0
	v_mov_b32_e32 v96, v0
	v_mov_b32_e32 v97, v0
	v_mov_b32_e32 v98, v0
	v_mov_b32_e32 v99, v0
	v_mov_b32_e32 v100, v0
	v_mov_b32_e32 v101, v0
	v_mov_b32_e32 v102, v0
	v_mov_b32_e32 v103, v0
	v_mov_b32_e32 v112, v0
	v_mov_b32_e32 v113, v0
	v_mov_b32_e32 v114, v0
	v_mov_b32_e32 v115, v0
	v_mov_b32_e32 v116, v0
	v_mov_b32_e32 v117, v0
	v_mov_b32_e32 v118, v0
	v_mov_b32_e32 v119, v0
	v_mov_b32_e32 v72, v0
	v_mov_b32_e32 v73, v0
	v_mov_b32_e32 v74, v0
	v_mov_b32_e32 v75, v0
	v_mov_b32_e32 v76, v0
	v_mov_b32_e32 v77, v0
	v_mov_b32_e32 v78, v0
	v_mov_b32_e32 v79, v0
	v_mov_b32_e32 v88, v0
	v_mov_b32_e32 v89, v0
	v_mov_b32_e32 v90, v0
	v_mov_b32_e32 v91, v0
	v_mov_b32_e32 v92, v0
	v_mov_b32_e32 v93, v0
	v_mov_b32_e32 v94, v0
	v_mov_b32_e32 v95, v0
	v_mov_b32_e32 v104, v0
	v_mov_b32_e32 v105, v0
	v_mov_b32_e32 v106, v0
	v_mov_b32_e32 v107, v0
	v_mov_b32_e32 v108, v0
	v_mov_b32_e32 v109, v0
	v_mov_b32_e32 v110, v0
	v_mov_b32_e32 v111, v0
	v_mov_b32_e32 v120, v0
	v_mov_b32_e32 v121, v0
	v_mov_b32_e32 v122, v0
	v_mov_b32_e32 v123, v0
	v_mov_b32_e32 v124, v0
	v_mov_b32_e32 v125, v0
	v_mov_b32_e32 v126, v0
	v_mov_b32_e32 v127, v0
	v_readfirstlane_b32 s32, v179
	s_nop 0
	s_lshr_b32 s32, s32, 8
	s_cmp_eq_u32 s32, 0
	s_cselect_b64 vcc, -1, 0
.LBB0_137:
	ds_read_b128 v[128:131], v172
	ds_read_b128 v[152:155], v172 offset:1024
	ds_read_b128 v[156:159], v172 offset:2048
	ds_read_b128 v[160:163], v172 offset:3072
	ds_read_b128 v[182:185], v173
	ds_read_b128 v[188:191], v173 offset:1024
	ds_read_b128 v[192:195], v173 offset:2048
	ds_read_b128 v[204:207], v173 offset:3072
	s_add_u32 s10, s4, 0xfff80080
	s_addc_u32 s11, s5, -1
	s_cmp_eq_u32 s78, 28
	s_cselect_b32 s67, s7, s11
	s_cselect_b32 s66, s9, s10
	s_cselect_b32 s11, s36, s77
	s_cselect_b32 s10, s73, s76
	v_lshl_add_u64 v[196:197], s[4:5], 0, v[144:145]
	s_add_i32 m0, s86, 0xc000
	ds_read_b128 v[208:211], v174
	ds_read_b128 v[212:215], v174 offset:1024
	ds_read_b128 v[216:219], v174 offset:2048
	ds_read_b128 v[222:225], v174 offset:3072
	ds_read_b128 v[226:229], v174 offset:4096
	ds_read_b128 v[230:233], v174 offset:5120
	ds_read_b128 v[234:237], v174 offset:6144
	ds_read_b128 v[238:241], v174 offset:7168
	global_load_lds_dwordx4 v[196:197], off
	v_lshl_add_u64 v[196:197], s[4:5], 0, v[146:147]
	s_add_i32 m0, s86, 0xe000
	s_nop 0
	global_load_lds_dwordx4 v[196:197], off
	s_cbranch_vccnz .Lkw_skip_137_0
	s_waitcnt vmcnt(8)
.Lkw_skip_137_0:
	s_waitcnt lgkmcnt(0)
	s_barrier
	s_setprio 1
	s_waitcnt lgkmcnt(0)
	v_mfma_f32_16x16x32_bf16 v[124:127], v[128:131], v[208:211], v[124:127]
	v_mfma_f32_16x16x32_bf16 v[120:123], v[156:159], v[208:211], v[120:123]
	v_mfma_f32_16x16x32_bf16 v[108:111], v[128:131], v[216:219], v[108:111]
	v_mfma_f32_16x16x32_bf16 v[104:107], v[156:159], v[216:219], v[104:107]
	v_mfma_f32_16x16x32_bf16 v[92:95], v[128:131], v[226:229], v[92:95]
	v_mfma_f32_16x16x32_bf16 v[88:91], v[156:159], v[226:229], v[88:91]
	v_mfma_f32_16x16x32_bf16 v[76:79], v[128:131], v[234:237], v[76:79]
	v_mfma_f32_16x16x32_bf16 v[72:75], v[156:159], v[234:237], v[72:75]
	v_mfma_f32_16x16x32_bf16 v[124:127], v[152:155], v[212:215], v[124:127]
	v_mfma_f32_16x16x32_bf16 v[120:123], v[160:163], v[212:215], v[120:123]
	v_mfma_f32_16x16x32_bf16 v[108:111], v[152:155], v[222:225], v[108:111]
	v_mfma_f32_16x16x32_bf16 v[104:107], v[160:163], v[222:225], v[104:107]
	v_mfma_f32_16x16x32_bf16 v[92:95], v[152:155], v[230:233], v[92:95]
	v_mfma_f32_16x16x32_bf16 v[88:91], v[160:163], v[230:233], v[88:91]
	v_mfma_f32_16x16x32_bf16 v[76:79], v[152:155], v[238:241], v[76:79]
	v_mfma_f32_16x16x32_bf16 v[72:75], v[160:163], v[238:241], v[72:75]
	s_setprio 0
	s_setprio 1
	v_mfma_f32_16x16x32_bf16 v[116:119], v[182:185], v[208:211], v[116:119]
	v_mfma_f32_16x16x32_bf16 v[112:115], v[192:195], v[208:211], v[112:115]
	v_mfma_f32_16x16x32_bf16 v[100:103], v[182:185], v[216:219], v[100:103]
	v_mfma_f32_16x16x32_bf16 v[96:99], v[192:195], v[216:219], v[96:99]
	v_mfma_f32_16x16x32_bf16 v[84:87], v[182:185], v[226:229], v[84:87]
	v_mfma_f32_16x16x32_bf16 v[80:83], v[192:195], v[226:229], v[80:83]
	v_mfma_f32_16x16x32_bf16 v[68:71], v[182:185], v[234:237], v[68:71]
	v_mfma_f32_16x16x32_bf16 v[64:67], v[192:195], v[234:237], v[64:67]
	v_mfma_f32_16x16x32_bf16 v[116:119], v[188:191], v[212:215], v[116:119]
	v_mfma_f32_16x16x32_bf16 v[112:115], v[204:207], v[212:215], v[112:115]
	v_mfma_f32_16x16x32_bf16 v[100:103], v[188:191], v[222:225], v[100:103]
	v_mfma_f32_16x16x32_bf16 v[96:99], v[204:207], v[222:225], v[96:99]
	v_mfma_f32_16x16x32_bf16 v[84:87], v[188:191], v[230:233], v[84:87]
	v_mfma_f32_16x16x32_bf16 v[80:83], v[204:207], v[230:233], v[80:83]
	v_mfma_f32_16x16x32_bf16 v[68:71], v[188:191], v[238:241], v[68:71]
	v_mfma_f32_16x16x32_bf16 v[64:67], v[204:207], v[238:241], v[64:67]
	s_setprio 0
	s_cbranch_vccz .Lkw_post_137_0
	s_waitcnt vmcnt(8)
.Lkw_post_137_0:
	s_barrier
	s_add_i32 s34, s53, s81
	v_lshl_add_u64 v[196:197], s[10:11], 0, v[134:135]
	s_mov_b32 m0, s34
	ds_read_b128 v[208:211], v174 offset:16384
	ds_read_b128 v[212:215], v174 offset:17408
	ds_read_b128 v[216:219], v174 offset:18432
	ds_read_b128 v[222:225], v174 offset:19456
	ds_read_b128 v[226:229], v174 offset:20480
	ds_read_b128 v[230:233], v174 offset:21504
	ds_read_b128 v[234:237], v174 offset:22528
	ds_read_b128 v[238:241], v174 offset:23552
	global_load_lds_dwordx4 v[196:197], off
	s_add_i32 m0, s34, 0x2000
	s_add_u32 s34, s10, 0x80000
	v_lshl_add_u64 v[242:243], s[10:11], 0, v[138:139]
	s_addc_u32 s35, s11, 0
	s_add_i32 s79, s19, s81
	global_load_lds_dwordx4 v[242:243], off
	v_lshl_add_u64 v[244:245], s[34:35], 0, v[134:135]
	s_mov_b32 m0, s79
	v_lshl_add_u64 v[246:247], s[66:67], 0, v[136:137]
	global_load_lds_dwordx4 v[244:245], off
	v_lshl_add_u64 v[244:245], s[34:35], 0, v[138:139]
	s_add_i32 m0, s79, 0x2000
	s_nop 0
	global_load_lds_dwordx4 v[244:245], off
	v_lshl_add_u64 v[244:245], s[66:67], 0, v[132:133]
	s_mov_b32 m0, s86
	s_nop 0
	global_load_lds_dwordx4 v[244:245], off
	s_mov_b32 m0, s87
	s_nop 0
	global_load_lds_dwordx4 v[246:247], off
	s_cbranch_vccnz .Lkw_skip_137_1
	s_waitcnt vmcnt(8)
.Lkw_skip_137_1:
	s_waitcnt lgkmcnt(0)
	s_barrier
	s_setprio 1
	s_waitcnt lgkmcnt(0)
	v_mfma_f32_16x16x32_bf16 v[60:63], v[128:131], v[208:211], v[60:63]
	v_mfma_f32_16x16x32_bf16 v[56:59], v[156:159], v[208:211], v[56:59]
	v_mfma_f32_16x16x32_bf16 v[44:47], v[128:131], v[216:219], v[44:47]
	v_mfma_f32_16x16x32_bf16 v[40:43], v[156:159], v[216:219], v[40:43]
	v_mfma_f32_16x16x32_bf16 v[28:31], v[128:131], v[226:229], v[28:31]
	v_mfma_f32_16x16x32_bf16 v[24:27], v[156:159], v[226:229], v[24:27]
	v_mfma_f32_16x16x32_bf16 v[12:15], v[128:131], v[234:237], v[12:15]
	v_mfma_f32_16x16x32_bf16 v[8:11], v[156:159], v[234:237], v[8:11]
	v_mfma_f32_16x16x32_bf16 v[60:63], v[152:155], v[212:215], v[60:63]
	v_mfma_f32_16x16x32_bf16 v[56:59], v[160:163], v[212:215], v[56:59]
	v_mfma_f32_16x16x32_bf16 v[44:47], v[152:155], v[222:225], v[44:47]
	v_mfma_f32_16x16x32_bf16 v[40:43], v[160:163], v[222:225], v[40:43]
	v_mfma_f32_16x16x32_bf16 v[28:31], v[152:155], v[230:233], v[28:31]
	v_mfma_f32_16x16x32_bf16 v[24:27], v[160:163], v[230:233], v[24:27]
	v_mfma_f32_16x16x32_bf16 v[12:15], v[152:155], v[238:241], v[12:15]
	v_mfma_f32_16x16x32_bf16 v[8:11], v[160:163], v[238:241], v[8:11]
	s_setprio 0
	s_setprio 1
	v_mfma_f32_16x16x32_bf16 v[52:55], v[182:185], v[208:211], v[52:55]
	v_mfma_f32_16x16x32_bf16 v[48:51], v[192:195], v[208:211], v[48:51]
	v_mfma_f32_16x16x32_bf16 v[36:39], v[182:185], v[216:219], v[36:39]
	v_mfma_f32_16x16x32_bf16 v[32:35], v[192:195], v[216:219], v[32:35]
	v_mfma_f32_16x16x32_bf16 v[20:23], v[182:185], v[226:229], v[20:23]
	v_mfma_f32_16x16x32_bf16 v[16:19], v[192:195], v[226:229], v[16:19]
	v_mfma_f32_16x16x32_bf16 v[4:7], v[182:185], v[234:237], v[4:7]
	v_mfma_f32_16x16x32_bf16 v[0:3], v[192:195], v[234:237], v[0:3]
	v_mfma_f32_16x16x32_bf16 v[52:55], v[188:191], v[212:215], v[52:55]
	v_mfma_f32_16x16x32_bf16 v[48:51], v[204:207], v[212:215], v[48:51]
	v_mfma_f32_16x16x32_bf16 v[36:39], v[188:191], v[222:225], v[36:39]
	v_mfma_f32_16x16x32_bf16 v[32:35], v[204:207], v[222:225], v[32:35]
	v_mfma_f32_16x16x32_bf16 v[20:23], v[188:191], v[230:233], v[20:23]
	v_mfma_f32_16x16x32_bf16 v[16:19], v[204:207], v[230:233], v[16:19]
	v_mfma_f32_16x16x32_bf16 v[4:7], v[188:191], v[238:241], v[4:7]
	v_mfma_f32_16x16x32_bf16 v[0:3], v[204:207], v[238:241], v[0:3]
	s_setprio 0
	s_cbranch_vccz .Lkw_post_137_1
	s_waitcnt vmcnt(8)
.Lkw_post_137_1:
	s_barrier
	s_add_i32 s79, 0, 0x18000
	v_add_u32_e32 v140, s79, v164
	s_add_i32 s84, 0, 0x1c000
	ds_read_b128 v[128:131], v140
	ds_read_b128 v[152:155], v140 offset:1024
	ds_read_b128 v[156:159], v140 offset:2048
	ds_read_b128 v[160:163], v140 offset:3072
	v_add_u32_e32 v140, s84, v164
	ds_read_b128 v[182:185], v140
	ds_read_b128 v[188:191], v140 offset:1024
	ds_read_b128 v[192:195], v140 offset:2048
	ds_read_b128 v[204:207], v140 offset:3072
	s_add_u32 s34, s66, 0x80000
	s_addc_u32 s35, s67, 0
	s_mov_b32 m0, s88
	v_lshl_add_u64 v[248:249], s[34:35], 0, v[132:133]
	ds_read_b128 v[208:211], v174 offset:32768
	ds_read_b128 v[212:215], v174 offset:33792
	ds_read_b128 v[216:219], v174 offset:34816
	ds_read_b128 v[222:225], v174 offset:35840
	ds_read_b128 v[226:229], v174 offset:36864
	ds_read_b128 v[230:233], v174 offset:37888
	ds_read_b128 v[234:237], v174 offset:38912
	ds_read_b128 v[238:241], v174 offset:39936
	global_load_lds_dwordx4 v[248:249], off
	v_lshl_add_u64 v[248:249], s[34:35], 0, v[136:137]
	s_mov_b32 m0, s89
	s_nop 0
	global_load_lds_dwordx4 v[248:249], off
	s_cbranch_vccnz .Lkw_skip_137_2
	s_waitcnt vmcnt(8)

.Lkw_post_137_2:
	s_barrier
	s_add_i32 s34, s79, s81
	v_lshl_add_u64 v[196:197], v[196:197], 0, s[50:51]
	s_mov_b32 m0, s34
	ds_read_b128 v[208:211], v174 offset:49152
	ds_read_b128 v[212:215], v174 offset:50176
	ds_read_b128 v[216:219], v174 offset:51200
	ds_read_b128 v[222:225], v174 offset:52224
	ds_read_b128 v[226:229], v174 offset:53248
	ds_read_b128 v[230:233], v174 offset:54272
	ds_read_b128 v[234:237], v174 offset:55296
	ds_read_b128 v[238:241], v174 offset:56320
	global_load_lds_dwordx4 v[196:197], off
	s_add_i32 m0, s34, 0x2000
	s_add_u32 s10, s10, 0x80080
	v_lshl_add_u64 v[196:197], v[242:243], 0, s[50:51]
	s_addc_u32 s11, s11, 0
	s_add_i32 s34, s84, s81
	global_load_lds_dwordx4 v[196:197], off
	v_lshl_add_u64 v[196:197], s[10:11], 0, v[134:135]
	s_mov_b32 m0, s34
	s_nop 0
	global_load_lds_dwordx4 v[196:197], off
	v_lshl_add_u64 v[196:197], s[10:11], 0, v[138:139]
	s_add_i32 m0, s34, 0x2000
	s_nop 0
	global_load_lds_dwordx4 v[196:197], off
	v_lshl_add_u64 v[196:197], v[244:245], 0, s[50:51]
	s_mov_b32 m0, s40
	s_nop 0
	global_load_lds_dwordx4 v[196:197], off
	v_lshl_add_u64 v[196:197], v[246:247], 0, s[50:51]
	s_mov_b32 m0, s41
	s_nop 0
	global_load_lds_dwordx4 v[196:197], off
	s_cbranch_vccnz .Lkw_skip_137_3
	s_waitcnt vmcnt(8)

; #define PG8_BAR __builtin_amdgcn_s_barrier()
; template <class Epi>
; __device__ __forceinline__ void gemm_phase(LAS unsigned char* lds, const Gemm g, const StaticOrder& S, const Epi& E) {
;     ...
;     for (;;) {
;         if constexpr (Epi::NPART == 2) {
;             const char* mA = cA + (size_t)K * 2; const char* mB = cB + (size_t)K * 2;
;             PG8_KLOOP(cA, cB, mA, mB)
;             E.mid(acc, cur, wr, wc, fr, fq);
;             cA = mA; cB = mB;
;         }
;         const bool has_next = S.next(ui + 1, nxt);
;         const char* nA = has_next ? (const char*)g.A + (size_t)nxt.pm * tstepA : cA; const char* nB = has_next ? (const char*)g.Bt + (size_t)nxt.pn * tstepB : cB;
;         PG8_KLOOP(cA, cB, nA, nB)
;         if (wr == 0) PG8_BAR;
.Lkw_post_137_3:
	s_barrier
	s_add_i32 s78, s78, 2
	s_add_u32 s4, s4, 0x100
	s_addc_u32 s5, s5, 0
	s_add_u32 s76, s76, 0x100
	s_addc_u32 s77, s77, 0
	s_cmp_gt_u32 s78, 29
	s_cbranch_scc0 .LBB0_137
	v_readlane_b32 s4, v250, 24
	v_readlane_b32 s5, v250, 25
	s_and_b64 vcc, exec, s[4:5]
	s_cbranch_vccz .LBB0_140
	s_barrier

; template <class Epi>
; __device__ __forceinline__ void gemm_phase(LAS unsigned char* lds, const Gemm g, const StaticOrder& S, const Epi& E) {
;     ...
;         for (int a = 0; a < 2; ++a)
; #pragma unroll
;             for (int b = 0; b < 2; ++b)
; #pragma unroll
;                 for (int m = 0; m < 4; ++m)
; #pragma unroll
;                     for (int n = 0; n < 2; ++n) acc[a][b][m][n] = (f32x4){0.f, 0.f, 0.f, 0.f};
;         cur = nxt; cA = nA; cB = nB; ++ui;
.LBB0_700:
	s_mov_b64 s[50:51], s[58:59]
	s_add_u32 s11, s50, 0x800
	s_mov_b64 s[52:53], s[56:57]
	s_addc_u32 s79, s51, 0
	s_add_u32 s62, s52, 0x800
	s_addc_u32 s63, s53, 0
	s_add_u32 s0, s50, 0x80080
	s_addc_u32 s1, s51, 0
	s_add_u32 s9, s52, 0x100
	v_mov_b32_e32 v0, 0
	s_addc_u32 s56, s53, 0
	s_mov_b32 s57, -2
	v_mov_b32_e32 v1, v0
	v_mov_b32_e32 v2, v0
	v_mov_b32_e32 v3, v0
	v_mov_b32_e32 v4, v0
	v_mov_b32_e32 v5, v0
	v_mov_b32_e32 v6, v0
	v_mov_b32_e32 v7, v0
	v_mov_b32_e32 v32, v0
	v_mov_b32_e32 v33, v0
	v_mov_b32_e32 v34, v0
	v_mov_b32_e32 v35, v0
	v_mov_b32_e32 v36, v0
	v_mov_b32_e32 v37, v0
	v_mov_b32_e32 v38, v0
	v_mov_b32_e32 v39, v0
	v_mov_b32_e32 v80, v0
	v_mov_b32_e32 v81, v0
	v_mov_b32_e32 v82, v0
	v_mov_b32_e32 v83, v0
	v_mov_b32_e32 v84, v0
	v_mov_b32_e32 v85, v0
	v_mov_b32_e32 v86, v0
	v_mov_b32_e32 v87, v0
	v_mov_b32_e32 v120, v0
	v_mov_b32_e32 v121, v0
	v_mov_b32_e32 v122, v0
	v_mov_b32_e32 v123, v0
	v_mov_b32_e32 v124, v0
	v_mov_b32_e32 v125, v0
	v_mov_b32_e32 v126, v0
	v_mov_b32_e32 v127, v0
	v_mov_b32_e32 v16, v0
	v_mov_b32_e32 v17, v0
	v_mov_b32_e32 v18, v0
	v_mov_b32_e32 v19, v0
	v_mov_b32_e32 v20, v0
	v_mov_b32_e32 v21, v0
	v_mov_b32_e32 v22, v0
	v_mov_b32_e32 v23, v0
	v_mov_b32_e32 v56, v0
	v_mov_b32_e32 v57, v0
	v_mov_b32_e32 v58, v0
	v_mov_b32_e32 v59, v0
	v_mov_b32_e32 v60, v0
	v_mov_b32_e32 v61, v0
	v_mov_b32_e32 v62, v0
	v_mov_b32_e32 v63, v0
	v_mov_b32_e32 v104, v0
	v_mov_b32_e32 v105, v0
	v_mov_b32_e32 v106, v0
	v_mov_b32_e32 v107, v0
	v_mov_b32_e32 v108, v0
	v_mov_b32_e32 v109, v0
	v_mov_b32_e32 v110, v0
	v_mov_b32_e32 v111, v0
	v_mov_b32_e32 v116, v0
	v_mov_b32_e32 v117, v0
	v_mov_b32_e32 v118, v0
	v_mov_b32_e32 v119, v0
	v_mov_b32_e32 v112, v0
	v_mov_b32_e32 v113, v0
	v_mov_b32_e32 v114, v0
	v_mov_b32_e32 v115, v0
	v_mov_b32_e32 v100, v0
	v_mov_b32_e32 v101, v0
	v_mov_b32_e32 v102, v0
	v_mov_b32_e32 v103, v0
	v_mov_b32_e32 v96, v0
	v_mov_b32_e32 v97, v0
	v_mov_b32_e32 v98, v0
	v_mov_b32_e32 v99, v0
	v_mov_b32_e32 v76, v0
	v_mov_b32_e32 v77, v0
	v_mov_b32_e32 v78, v0
	v_mov_b32_e32 v79, v0
	v_mov_b32_e32 v72, v0
	v_mov_b32_e32 v73, v0
	v_mov_b32_e32 v74, v0
	v_mov_b32_e32 v75, v0
	v_mov_b32_e32 v52, v0
	v_mov_b32_e32 v53, v0
	v_mov_b32_e32 v54, v0
	v_mov_b32_e32 v55, v0
	v_mov_b32_e32 v48, v0
	v_mov_b32_e32 v49, v0
	v_mov_b32_e32 v50, v0
	v_mov_b32_e32 v51, v0
	v_mov_b32_e32 v24, v0
	v_mov_b32_e32 v25, v0
	v_mov_b32_e32 v26, v0
	v_mov_b32_e32 v27, v0
	v_mov_b32_e32 v28, v0
	v_mov_b32_e32 v29, v0
	v_mov_b32_e32 v30, v0
	v_mov_b32_e32 v31, v0
	v_mov_b32_e32 v92, v0
	v_mov_b32_e32 v93, v0
	v_mov_b32_e32 v94, v0
	v_mov_b32_e32 v95, v0
	v_mov_b32_e32 v88, v0
	v_mov_b32_e32 v89, v0
	v_mov_b32_e32 v90, v0
	v_mov_b32_e32 v91, v0
	v_mov_b32_e32 v68, v0
	v_mov_b32_e32 v69, v0
	v_mov_b32_e32 v70, v0
	v_mov_b32_e32 v71, v0
	v_mov_b32_e32 v64, v0
	v_mov_b32_e32 v65, v0
	v_mov_b32_e32 v66, v0
	v_mov_b32_e32 v67, v0
	v_mov_b32_e32 v44, v0
	v_mov_b32_e32 v45, v0
	v_mov_b32_e32 v46, v0
	v_mov_b32_e32 v47, v0
	v_mov_b32_e32 v40, v0
	v_mov_b32_e32 v41, v0
	v_mov_b32_e32 v42, v0
	v_mov_b32_e32 v43, v0
	v_mov_b32_e32 v12, v0
	v_mov_b32_e32 v13, v0
	v_mov_b32_e32 v14, v0
	v_mov_b32_e32 v15, v0
	v_mov_b32_e32 v8, v0
	v_mov_b32_e32 v9, v0
	v_mov_b32_e32 v10, v0
	v_mov_b32_e32 v11, v0
	v_readfirstlane_b32 s32, v179
	s_nop 0
	s_lshr_b32 s32, s32, 8
	s_cmp_eq_u32 s32, 0
	s_cselect_b64 vcc, -1, 0
.LBB0_701:
	ds_read_b128 v[148:151], v144
	ds_read_b128 v[152:155], v144 offset:1024
	ds_read_b128 v[156:159], v144 offset:2048
	ds_read_b128 v[160:163], v144 offset:3072
	ds_read_b128 v[164:167], v145
	ds_read_b128 v[168:171], v145 offset:1024
	ds_read_b128 v[172:175], v145 offset:2048
	ds_read_b128 v[180:183], v145 offset:3072
	s_add_u32 s34, s0, 0xfff80080
	s_addc_u32 s35, s1, -1
	s_cmp_eq_u32 s57, 12
	s_cselect_b32 s55, s79, s35
	s_cselect_b32 s54, s11, s34
	s_cselect_b32 s49, s63, s56
	s_cselect_b32 s48, s62, s9
	s_mov_b32 m0, s66
	v_lshl_add_u64 v[138:139], s[0:1], 0, v[128:129]
	ds_read_b128 v[184:187], v146
	ds_read_b128 v[188:191], v146 offset:1024
	ds_read_b128 v[192:195], v146 offset:2048
	ds_read_b128 v[196:199], v146 offset:3072
	ds_read_b128 v[200:203], v146 offset:4096
	ds_read_b128 v[204:207], v146 offset:5120
	ds_read_b128 v[208:211], v146 offset:6144
	ds_read_b128 v[212:215], v146 offset:7168
	global_load_lds_dwordx4 v[138:139], off
	v_lshl_add_u64 v[138:139], s[0:1], 0, v[132:133]
	s_mov_b32 m0, s67
	s_nop 0
	global_load_lds_dwordx4 v[138:139], off
	s_cbranch_vccnz .Lkw_skip_701_0
	s_waitcnt vmcnt(8)
.Lkw_skip_701_0:
	s_waitcnt lgkmcnt(0)
	s_barrier
	s_setprio 1
	s_waitcnt lgkmcnt(0)
	v_mfma_f32_16x16x32_bf16 v[8:11], v[148:151], v[184:187], v[8:11]
	v_mfma_f32_16x16x32_bf16 v[12:15], v[156:159], v[184:187], v[12:15]
	v_mfma_f32_16x16x32_bf16 v[40:43], v[148:151], v[192:195], v[40:43]
	v_mfma_f32_16x16x32_bf16 v[44:47], v[156:159], v[192:195], v[44:47]
	v_mfma_f32_16x16x32_bf16 v[64:67], v[148:151], v[200:203], v[64:67]
	v_mfma_f32_16x16x32_bf16 v[68:71], v[156:159], v[200:203], v[68:71]
	v_mfma_f32_16x16x32_bf16 v[88:91], v[148:151], v[208:211], v[88:91]
	v_mfma_f32_16x16x32_bf16 v[92:95], v[156:159], v[208:211], v[92:95]
	v_mfma_f32_16x16x32_bf16 v[8:11], v[152:155], v[188:191], v[8:11]
	v_mfma_f32_16x16x32_bf16 v[12:15], v[160:163], v[188:191], v[12:15]
	v_mfma_f32_16x16x32_bf16 v[40:43], v[152:155], v[196:199], v[40:43]
	v_mfma_f32_16x16x32_bf16 v[44:47], v[160:163], v[196:199], v[44:47]
	v_mfma_f32_16x16x32_bf16 v[64:67], v[152:155], v[204:207], v[64:67]
	v_mfma_f32_16x16x32_bf16 v[68:71], v[160:163], v[204:207], v[68:71]
	v_mfma_f32_16x16x32_bf16 v[88:91], v[152:155], v[212:215], v[88:91]
	v_mfma_f32_16x16x32_bf16 v[92:95], v[160:163], v[212:215], v[92:95]
	s_setprio 0
	s_setprio 1
	v_mfma_f32_16x16x32_bf16 v[28:31], v[164:167], v[184:187], v[28:31]
	v_mfma_f32_16x16x32_bf16 v[24:27], v[172:175], v[184:187], v[24:27]
	v_mfma_f32_16x16x32_bf16 v[48:51], v[164:167], v[192:195], v[48:51]
	v_mfma_f32_16x16x32_bf16 v[52:55], v[172:175], v[192:195], v[52:55]
	v_mfma_f32_16x16x32_bf16 v[72:75], v[164:167], v[200:203], v[72:75]
	v_mfma_f32_16x16x32_bf16 v[76:79], v[172:175], v[200:203], v[76:79]
	v_mfma_f32_16x16x32_bf16 v[96:99], v[164:167], v[208:211], v[96:99]
	v_mfma_f32_16x16x32_bf16 v[100:103], v[172:175], v[208:211], v[100:103]
	v_mfma_f32_16x16x32_bf16 v[28:31], v[168:171], v[188:191], v[28:31]
	v_mfma_f32_16x16x32_bf16 v[24:27], v[180:183], v[188:191], v[24:27]
	v_mfma_f32_16x16x32_bf16 v[48:51], v[168:171], v[196:199], v[48:51]
	v_mfma_f32_16x16x32_bf16 v[52:55], v[180:183], v[196:199], v[52:55]
	v_mfma_f32_16x16x32_bf16 v[72:75], v[168:171], v[204:207], v[72:75]
	v_mfma_f32_16x16x32_bf16 v[76:79], v[180:183], v[204:207], v[76:79]
	v_mfma_f32_16x16x32_bf16 v[96:99], v[168:171], v[212:215], v[96:99]
	v_mfma_f32_16x16x32_bf16 v[100:103], v[180:183], v[212:215], v[100:103]
	s_setprio 0
	s_cbranch_vccz .Lkw_post_701_0
	s_waitcnt vmcnt(8)
.Lkw_post_701_0:
	s_barrier
	s_mov_b32 m0, s72
	v_lshl_add_u64 v[216:217], s[48:49], 0, v[130:131]
	s_add_u32 s34, s48, 0x80000
	ds_read_b128 v[184:187], v146 offset:16384
	ds_read_b128 v[188:191], v146 offset:17408
	ds_read_b128 v[192:195], v146 offset:18432
	ds_read_b128 v[196:199], v146 offset:19456
	ds_read_b128 v[200:203], v146 offset:20480
	ds_read_b128 v[204:207], v146 offset:21504
	ds_read_b128 v[208:211], v146 offset:22528
	ds_read_b128 v[212:215], v146 offset:23552
	global_load_lds_dwordx4 v[216:217], off
	v_lshl_add_u64 v[218:219], s[48:49], 0, v[134:135]
	s_mov_b32 m0, s73
	s_addc_u32 s35, s49, 0
	global_load_lds_dwordx4 v[218:219], off
	v_lshl_add_u64 v[138:139], s[34:35], 0, v[130:131]
	s_mov_b32 m0, s74
	v_lshl_add_u64 v[222:223], s[54:55], 0, v[128:129]
	global_load_lds_dwordx4 v[138:139], off
	v_lshl_add_u64 v[138:139], s[34:35], 0, v[134:135]
	s_mov_b32 m0, s76
	v_lshl_add_u64 v[224:225], s[54:55], 0, v[132:133]
	global_load_lds_dwordx4 v[138:139], off
	s_mov_b32 m0, s36
	s_nop 0
	global_load_lds_dwordx4 v[222:223], off
	s_mov_b32 m0, s37
	s_nop 0
	global_load_lds_dwordx4 v[224:225], off
	s_cbranch_vccnz .Lkw_skip_701_1
	s_waitcnt vmcnt(8)
.Lkw_skip_701_1:
	s_waitcnt lgkmcnt(0)
	s_barrier
	s_setprio 1
	s_waitcnt lgkmcnt(0)
	v_mfma_f32_16x16x32_bf16 v[112:115], v[148:151], v[184:187], v[112:115]
	v_mfma_f32_16x16x32_bf16 v[116:119], v[156:159], v[184:187], v[116:119]
	v_mfma_f32_16x16x32_bf16 v[108:111], v[148:151], v[192:195], v[108:111]
	v_mfma_f32_16x16x32_bf16 v[104:107], v[156:159], v[192:195], v[104:107]
	v_mfma_f32_16x16x32_bf16 v[60:63], v[148:151], v[200:203], v[60:63]
	v_mfma_f32_16x16x32_bf16 v[56:59], v[156:159], v[200:203], v[56:59]
	v_mfma_f32_16x16x32_bf16 v[20:23], v[148:151], v[208:211], v[20:23]
	v_mfma_f32_16x16x32_bf16 v[16:19], v[156:159], v[208:211], v[16:19]
	v_mfma_f32_16x16x32_bf16 v[112:115], v[152:155], v[188:191], v[112:115]
	v_mfma_f32_16x16x32_bf16 v[116:119], v[160:163], v[188:191], v[116:119]
	v_mfma_f32_16x16x32_bf16 v[108:111], v[152:155], v[196:199], v[108:111]
	v_mfma_f32_16x16x32_bf16 v[104:107], v[160:163], v[196:199], v[104:107]
	v_mfma_f32_16x16x32_bf16 v[60:63], v[152:155], v[204:207], v[60:63]
	v_mfma_f32_16x16x32_bf16 v[56:59], v[160:163], v[204:207], v[56:59]
	v_mfma_f32_16x16x32_bf16 v[20:23], v[152:155], v[212:215], v[20:23]
	v_mfma_f32_16x16x32_bf16 v[16:19], v[160:163], v[212:215], v[16:19]
	s_setprio 0
	s_setprio 1
	v_mfma_f32_16x16x32_bf16 v[124:127], v[164:167], v[184:187], v[124:127]
	v_mfma_f32_16x16x32_bf16 v[120:123], v[172:175], v[184:187], v[120:123]
	v_mfma_f32_16x16x32_bf16 v[84:87], v[164:167], v[192:195], v[84:87]
	v_mfma_f32_16x16x32_bf16 v[80:83], v[172:175], v[192:195], v[80:83]
	v_mfma_f32_16x16x32_bf16 v[36:39], v[164:167], v[200:203], v[36:39]
	v_mfma_f32_16x16x32_bf16 v[32:35], v[172:175], v[200:203], v[32:35]
	v_mfma_f32_16x16x32_bf16 v[4:7], v[164:167], v[208:211], v[4:7]
	v_mfma_f32_16x16x32_bf16 v[0:3], v[172:175], v[208:211], v[0:3]
	v_mfma_f32_16x16x32_bf16 v[124:127], v[168:171], v[188:191], v[124:127]
	v_mfma_f32_16x16x32_bf16 v[120:123], v[180:183], v[188:191], v[120:123]
	v_mfma_f32_16x16x32_bf16 v[84:87], v[168:171], v[196:199], v[84:87]
	v_mfma_f32_16x16x32_bf16 v[80:83], v[180:183], v[196:199], v[80:83]
	v_mfma_f32_16x16x32_bf16 v[36:39], v[168:171], v[204:207], v[36:39]
	v_mfma_f32_16x16x32_bf16 v[32:35], v[180:183], v[204:207], v[32:35]
	v_mfma_f32_16x16x32_bf16 v[4:7], v[168:171], v[212:215], v[4:7]
	v_mfma_f32_16x16x32_bf16 v[0:3], v[180:183], v[212:215], v[0:3]
	s_setprio 0
	s_cbranch_vccz .Lkw_post_701_1
	s_waitcnt vmcnt(8)
.Lkw_post_701_1:
	s_barrier
	s_add_i32 s82, 0, 0x1c000
	v_add_u32_e32 v138, s82, v140
	ds_read_b128 v[148:151], v147
	ds_read_b128 v[152:155], v147 offset:1024
	ds_read_b128 v[156:159], v147 offset:2048
	ds_read_b128 v[160:163], v147 offset:3072
	ds_read_b128 v[164:167], v138
	ds_read_b128 v[168:171], v138 offset:1024
	ds_read_b128 v[172:175], v138 offset:2048
	ds_read_b128 v[180:183], v138 offset:3072
	s_add_u32 s34, s54, 0x80000
	s_addc_u32 s35, s55, 0
	s_mov_b32 m0, s40
	v_lshl_add_u64 v[226:227], s[34:35], 0, v[128:129]
	ds_read_b128 v[184:187], v146 offset:32768
	ds_read_b128 v[188:191], v146 offset:33792
	ds_read_b128 v[192:195], v146 offset:34816
	ds_read_b128 v[196:199], v146 offset:35840
	ds_read_b128 v[200:203], v146 offset:36864
	ds_read_b128 v[204:207], v146 offset:37888
	ds_read_b128 v[208:211], v146 offset:38912
	ds_read_b128 v[212:215], v146 offset:39936
	global_load_lds_dwordx4 v[226:227], off
	v_lshl_add_u64 v[226:227], s[34:35], 0, v[132:133]
	s_mov_b32 m0, s41
	s_nop 0
	global_load_lds_dwordx4 v[226:227], off
	s_cbranch_vccnz .Lkw_skip_701_2
	s_waitcnt vmcnt(8)

.Lkw_post_701_2:
	s_barrier
	s_add_i32 s80, s77, s14
	s_add_i32 s81, s80, 0x2000
	v_lshl_add_u64 v[216:217], v[216:217], 0, s[22:23]
	s_mov_b32 m0, s80
	s_add_u32 s34, s48, 0x80080
	ds_read_b128 v[184:187], v146 offset:49152
	ds_read_b128 v[188:191], v146 offset:50176
	ds_read_b128 v[192:195], v146 offset:51200
	ds_read_b128 v[196:199], v146 offset:52224
	ds_read_b128 v[200:203], v146 offset:53248
	ds_read_b128 v[204:207], v146 offset:54272
	ds_read_b128 v[208:211], v146 offset:55296
	ds_read_b128 v[212:215], v146 offset:56320
	global_load_lds_dwordx4 v[216:217], off
	v_lshl_add_u64 v[216:217], v[218:219], 0, s[22:23]
	s_mov_b32 m0, s81
	s_addc_u32 s35, s49, 0
	s_add_i32 s82, s82, s14
	global_load_lds_dwordx4 v[216:217], off
	v_lshl_add_u64 v[216:217], s[34:35], 0, v[130:131]
	s_mov_b32 m0, s82
	s_add_i32 s83, s82, 0x2000
	global_load_lds_dwordx4 v[216:217], off
	v_lshl_add_u64 v[216:217], s[34:35], 0, v[134:135]
	s_mov_b32 m0, s83
	s_nop 0
	global_load_lds_dwordx4 v[216:217], off
	v_lshl_add_u64 v[216:217], v[222:223], 0, s[22:23]
	s_mov_b32 m0, s43
	s_nop 0
	global_load_lds_dwordx4 v[216:217], off
	v_lshl_add_u64 v[216:217], v[224:225], 0, s[22:23]
	s_mov_b32 m0, s64
	s_nop 0
	global_load_lds_dwordx4 v[216:217], off
	s_cbranch_vccnz .Lkw_skip_701_3
	s_waitcnt vmcnt(8)

; template <class Epi>
; __device__ __forceinline__ void gemm_phase(LAS unsigned char* lds, const Gemm g, const StaticOrder& S, const Epi& E) {
;     ...
;     for (;;) {
;         if constexpr (Epi::NPART == 2) {
;             const char* mA = cA + (size_t)K * 2; const char* mB = cB + (size_t)K * 2;
;             PG8_KLOOP(cA, cB, mA, mB)
;             E.mid(acc, cur, wr, wc, fr, fq);
;             cA = mA; cB = mB;
;         unsigned lo_ = (unsigned)((wr * 64 + fr) * PLD + wc * 32 + 8 * fq) * 2u; asm volatile("" : "+v"(lo_));
;         const char* pb = (const char*)proj + (((size_t)u.pm * 256 + u.ra) * PLD + u.pn * 256 + u.cb) * 2;
; #pragma unroll
;         for (int ai = 0; ai < NAI; ++ai)
; #pragma unroll
;             for (int m = 0; m < 4; ++m) {
; #pragma unroll
;                 for (int bj = 0; bj < NBJ; ++bj) {
;                     const unsigned off = lo_ + (unsigned)(((ai * 128 + m * 16) * PLD + bj * 128) * 2);
;                     const u32x4 rv = *(const u32x4*)(pb + off + PC_GA * 2);
;                     acc[ai][bj][m][0][0] *= bflo(rv[0]); acc[ai][bj][m][0][1] *= bfhi(rv[0]); acc[ai][bj][m][0][2] *= bflo(rv[1]); acc[ai][bj][m][0][3] *= bfhi(rv[1]);
;                     acc[ai][bj][m][1][0] *= bflo(rv[2]); acc[ai][bj][m][1][1] *= bfhi(rv[2]); acc[ai][bj][m][1][2] *= bflo(rv[3]); acc[ai][bj][m][1][3] *= bfhi(rv[3]);
;                     asm volatile("" : "+v"(acc[ai][bj][m][0]), "+v"(acc[ai][bj][m][1]) :: "memory");
;                 }
.Lkw_post_701_3:
	s_barrier
	s_add_i32 s57, s57, 2
	s_add_u32 s0, s0, 0x100
	s_addc_u32 s1, s1, 0
	s_add_u32 s9, s9, 0x100
	s_addc_u32 s56, s56, 0
	s_cmp_gt_u32 s57, 13
	s_cbranch_scc0 .LBB0_701
	s_lshl_b32 s54, s10, 8
	s_mul_i32 s0, s8, 0x240000
	s_ashr_i32 s55, s54, 31
	s_mul_hi_i32 s1, s8, 0x240000
	s_add_u32 s0, s0, s54
	s_addc_u32 s1, s1, s55
	s_lshl_b64 s[0:1], s[0:1], 1
	s_add_u32 s48, s16, s0
	s_addc_u32 s49, s17, s1
	s_add_i32 s78, s78, 1
	s_mul_i32 s0, s78, s65
	s_mul_hi_u32 s1, s78, s3
	s_add_i32 s1, s1, s0
	s_mul_i32 s0, s78, s3
	s_add_u32 s56, s0, s2
	s_addc_u32 s57, s1, s15
	s_mov_b32 s9, s8
	v_mov_b32_e32 v136, v141
	v_lshl_add_u64 v[148:149], s[48:49], 0, v[136:137]
	v_add_co_u32_e32 v148, vcc, s42, v148
	s_mov_b32 s85, 0
	s_nop 0
	v_addc_co_u32_e32 v149, vcc, 0, v149, vcc
	global_load_dwordx4 v[180:183], v[148:149], off offset:2048
	s_mov_b32 s84, 0x100
	v_lshl_add_u64 v[150:151], v[148:149], 0, s[84:85]
	global_load_dwordx4 v[184:187], v[150:151], off offset:2048
	s_mov_b32 s84, 0x48000
	v_lshl_add_u64 v[152:153], v[148:149], 0, s[84:85]
	global_load_dwordx4 v[188:191], v[152:153], off offset:2048
	s_mov_b32 s84, 0x48100
	v_lshl_add_u64 v[150:151], v[148:149], 0, s[84:85]
	global_load_dwordx4 v[192:195], v[150:151], off offset:2048
	s_mov_b32 s84, 0x90000
	v_lshl_add_u64 v[152:153], v[148:149], 0, s[84:85]
	global_load_dwordx4 v[196:199], v[152:153], off offset:2048
	s_mov_b32 s84, 0x90100
	v_lshl_add_u64 v[150:151], v[148:149], 0, s[84:85]
	global_load_dwordx4 v[200:203], v[150:151], off offset:2048
	s_mov_b32 s84, 0xd8000
	v_lshl_add_u64 v[152:153], v[148:149], 0, s[84:85]
	global_load_dwordx4 v[204:207], v[152:153], off offset:2048
	s_mov_b32 s84, 0xd8100
	v_lshl_add_u64 v[150:151], v[148:149], 0, s[84:85]
	global_load_dwordx4 v[208:211], v[150:151], off offset:2048
	s_mov_b32 s84, 0x240000
	v_lshl_add_u64 v[152:153], v[148:149], 0, s[84:85]
	global_load_dwordx4 v[212:215], v[152:153], off offset:2048
	s_mov_b32 s84, 0x240100
	v_lshl_add_u64 v[150:151], v[148:149], 0, s[84:85]
	global_load_dwordx4 v[216:219], v[150:151], off offset:2048
	s_mov_b32 s84, 0x288000
	v_lshl_add_u64 v[152:153], v[148:149], 0, s[84:85]
	global_load_dwordx4 v[224:227], v[152:153], off offset:2048
	s_mov_b32 s84, 0x288100
	v_lshl_add_u64 v[150:151], v[148:149], 0, s[84:85]
	global_load_dwordx4 v[228:231], v[150:151], off offset:2048
	s_mov_b32 s84, 0x2d0000
	v_lshl_add_u64 v[152:153], v[148:149], 0, s[84:85]
	global_load_dwordx4 v[232:235], v[152:153], off offset:2048
	s_mov_b32 s84, 0x2d0100
	v_lshl_add_u64 v[150:151], v[148:149], 0, s[84:85]
	global_load_dwordx4 v[236:239], v[150:151], off offset:2048
	s_mov_b32 s84, 0x318000
	v_lshl_add_u64 v[152:153], v[148:149], 0, s[84:85]
	global_load_dwordx4 v[240:243], v[152:153], off offset:2048
	s_mov_b32 s84, 0x318100
	v_lshl_add_u64 v[150:151], v[148:149], 0, s[84:85]
	global_load_dwordx4 v[244:247], v[150:151], off offset:2048
	s_waitcnt vmcnt(15)
	v_lshlrev_b32_e32 v148, 16, v180
	v_and_b32_e32 v149, 0xffff0000, v180
	v_pk_mul_f32 v[8:9], v[8:9], v[148:149]
	v_lshlrev_b32_e32 v150, 16, v181
	v_and_b32_e32 v151, 0xffff0000, v181
	v_pk_mul_f32 v[10:11], v[10:11], v[150:151]
	v_lshlrev_b32_e32 v148, 16, v182
	v_and_b32_e32 v149, 0xffff0000, v182
	v_pk_mul_f32 v[12:13], v[12:13], v[148:149]
	v_lshlrev_b32_e32 v150, 16, v183
	v_and_b32_e32 v151, 0xffff0000, v183
	v_pk_mul_f32 v[14:15], v[14:15], v[150:151]
	s_waitcnt vmcnt(14)
	v_lshlrev_b32_e32 v148, 16, v184
	v_and_b32_e32 v149, 0xffff0000, v184
	v_pk_mul_f32 v[28:29], v[28:29], v[148:149]
	v_lshlrev_b32_e32 v150, 16, v185
	v_and_b32_e32 v151, 0xffff0000, v185
	v_pk_mul_f32 v[30:31], v[30:31], v[150:151]
	v_lshlrev_b32_e32 v148, 16, v186
	v_and_b32_e32 v149, 0xffff0000, v186
	v_pk_mul_f32 v[24:25], v[24:25], v[148:149]
	v_lshlrev_b32_e32 v150, 16, v187
	v_and_b32_e32 v151, 0xffff0000, v187
	v_pk_mul_f32 v[26:27], v[26:27], v[150:151]
	s_waitcnt vmcnt(13)
	v_lshlrev_b32_e32 v148, 16, v188
	v_and_b32_e32 v149, 0xffff0000, v188
	v_pk_mul_f32 v[40:41], v[40:41], v[148:149]
	v_lshlrev_b32_e32 v150, 16, v189
	v_and_b32_e32 v151, 0xffff0000, v189
	v_pk_mul_f32 v[42:43], v[42:43], v[150:151]
	v_lshlrev_b32_e32 v148, 16, v190
	v_and_b32_e32 v149, 0xffff0000, v190
	v_pk_mul_f32 v[44:45], v[44:45], v[148:149]
	v_lshlrev_b32_e32 v150, 16, v191
	v_and_b32_e32 v151, 0xffff0000, v191
	v_pk_mul_f32 v[46:47], v[46:47], v[150:151]
	s_waitcnt vmcnt(12)
	v_lshlrev_b32_e32 v148, 16, v192
	v_and_b32_e32 v149, 0xffff0000, v192
	v_pk_mul_f32 v[48:49], v[48:49], v[148:149]
	v_lshlrev_b32_e32 v150, 16, v193
	v_and_b32_e32 v151, 0xffff0000, v193
	v_pk_mul_f32 v[50:51], v[50:51], v[150:151]
	v_lshlrev_b32_e32 v148, 16, v194
	v_and_b32_e32 v149, 0xffff0000, v194
	v_pk_mul_f32 v[52:53], v[52:53], v[148:149]
	v_lshlrev_b32_e32 v150, 16, v195
	v_and_b32_e32 v151, 0xffff0000, v195
	v_pk_mul_f32 v[54:55], v[54:55], v[150:151]
	s_waitcnt vmcnt(11)
	v_lshlrev_b32_e32 v148, 16, v196
	v_and_b32_e32 v149, 0xffff0000, v196
	v_pk_mul_f32 v[64:65], v[64:65], v[148:149]
	v_lshlrev_b32_e32 v150, 16, v197
	v_and_b32_e32 v151, 0xffff0000, v197
	v_pk_mul_f32 v[66:67], v[66:67], v[150:151]
	v_lshlrev_b32_e32 v148, 16, v198
	v_and_b32_e32 v149, 0xffff0000, v198
	v_pk_mul_f32 v[68:69], v[68:69], v[148:149]
	v_lshlrev_b32_e32 v150, 16, v199
	v_and_b32_e32 v151, 0xffff0000, v199
	v_pk_mul_f32 v[70:71], v[70:71], v[150:151]
	s_waitcnt vmcnt(10)
	v_lshlrev_b32_e32 v148, 16, v200
	v_and_b32_e32 v149, 0xffff0000, v200
	v_pk_mul_f32 v[72:73], v[72:73], v[148:149]
	v_lshlrev_b32_e32 v150, 16, v201
	v_and_b32_e32 v151, 0xffff0000, v201
	v_pk_mul_f32 v[74:75], v[74:75], v[150:151]
	v_lshlrev_b32_e32 v148, 16, v202
	v_and_b32_e32 v149, 0xffff0000, v202
	v_pk_mul_f32 v[76:77], v[76:77], v[148:149]
	v_lshlrev_b32_e32 v150, 16, v203
	v_and_b32_e32 v151, 0xffff0000, v203
	v_pk_mul_f32 v[78:79], v[78:79], v[150:151]
	s_waitcnt vmcnt(9)
;     __device__ bool next(int i, Unit& u) const {
;         const long L = (long)i * G + c; if (L >= lim) return false;
;         unit_of((int)L, u); return true;
;     ...
;                     acc[ai][bj][m][0][0] *= bflo(rv[0]); acc[ai][bj][m][0][1] *= bfhi(rv[0]); acc[ai][bj][m][0][2] *= bflo(rv[1]); acc[ai][bj][m][0][3] *= bfhi(rv[1]);
;                     acc[ai][bj][m][1][0] *= bflo(rv[2]); acc[ai][bj][m][1][1] *= bfhi(rv[2]); acc[ai][bj][m][1][2] *= bflo(rv[3]); acc[ai][bj][m][1][3] *= bfhi(rv[3]);
;                     asm volatile("" : "+v"(acc[ai][bj][m][0]), "+v"(acc[ai][bj][m][1]) :: "memory");
	v_lshlrev_b32_e32 v148, 16, v204
	v_and_b32_e32 v149, 0xffff0000, v204
	v_pk_mul_f32 v[88:89], v[88:89], v[148:149]
	v_lshlrev_b32_e32 v150, 16, v205
	v_and_b32_e32 v151, 0xffff0000, v205
	v_pk_mul_f32 v[90:91], v[90:91], v[150:151]
	v_lshlrev_b32_e32 v148, 16, v206
	v_and_b32_e32 v149, 0xffff0000, v206
	v_pk_mul_f32 v[92:93], v[92:93], v[148:149]
	v_lshlrev_b32_e32 v150, 16, v207
	v_and_b32_e32 v151, 0xffff0000, v207
	v_pk_mul_f32 v[94:95], v[94:95], v[150:151]
	s_waitcnt vmcnt(8)
	v_lshlrev_b32_e32 v148, 16, v208
	v_and_b32_e32 v149, 0xffff0000, v208
	v_pk_mul_f32 v[96:97], v[96:97], v[148:149]
	v_lshlrev_b32_e32 v150, 16, v209
	v_and_b32_e32 v151, 0xffff0000, v209
	v_pk_mul_f32 v[98:99], v[98:99], v[150:151]
	v_lshlrev_b32_e32 v148, 16, v210
	v_and_b32_e32 v149, 0xffff0000, v210
	v_pk_mul_f32 v[100:101], v[100:101], v[148:149]
	v_lshlrev_b32_e32 v150, 16, v211
	v_and_b32_e32 v151, 0xffff0000, v211
	v_pk_mul_f32 v[102:103], v[102:103], v[150:151]
	s_waitcnt vmcnt(7)
	v_lshlrev_b32_e32 v148, 16, v212
	v_and_b32_e32 v149, 0xffff0000, v212
	v_pk_mul_f32 v[112:113], v[112:113], v[148:149]
	v_lshlrev_b32_e32 v150, 16, v213
	v_and_b32_e32 v151, 0xffff0000, v213
	v_pk_mul_f32 v[114:115], v[114:115], v[150:151]
	v_lshlrev_b32_e32 v148, 16, v214
	v_and_b32_e32 v149, 0xffff0000, v214
	v_pk_mul_f32 v[116:117], v[116:117], v[148:149]
	v_lshlrev_b32_e32 v150, 16, v215
	v_and_b32_e32 v151, 0xffff0000, v215
	v_pk_mul_f32 v[118:119], v[118:119], v[150:151]
	s_waitcnt vmcnt(6)
	v_lshlrev_b32_e32 v148, 16, v216
	v_and_b32_e32 v149, 0xffff0000, v216
	v_pk_mul_f32 v[124:125], v[124:125], v[148:149]
	v_lshlrev_b32_e32 v150, 16, v217
	v_and_b32_e32 v151, 0xffff0000, v217
	v_pk_mul_f32 v[126:127], v[126:127], v[150:151]
	v_lshlrev_b32_e32 v148, 16, v218
	v_and_b32_e32 v149, 0xffff0000, v218
	v_pk_mul_f32 v[120:121], v[120:121], v[148:149]
	v_lshlrev_b32_e32 v150, 16, v219
	v_and_b32_e32 v151, 0xffff0000, v219
	v_pk_mul_f32 v[122:123], v[122:123], v[150:151]
	s_waitcnt vmcnt(5)
	v_lshlrev_b32_e32 v148, 16, v224
	v_and_b32_e32 v149, 0xffff0000, v224
	v_pk_mul_f32 v[108:109], v[108:109], v[148:149]
	v_lshlrev_b32_e32 v150, 16, v225
	v_and_b32_e32 v151, 0xffff0000, v225
	v_pk_mul_f32 v[110:111], v[110:111], v[150:151]
	v_lshlrev_b32_e32 v148, 16, v226
	v_and_b32_e32 v149, 0xffff0000, v226
	v_pk_mul_f32 v[104:105], v[104:105], v[148:149]
	v_lshlrev_b32_e32 v150, 16, v227
	v_and_b32_e32 v151, 0xffff0000, v227
	v_pk_mul_f32 v[106:107], v[106:107], v[150:151]
	s_waitcnt vmcnt(4)
	v_lshlrev_b32_e32 v148, 16, v228
	v_and_b32_e32 v149, 0xffff0000, v228
	v_pk_mul_f32 v[84:85], v[84:85], v[148:149]
	v_lshlrev_b32_e32 v150, 16, v229
	v_and_b32_e32 v151, 0xffff0000, v229
	v_pk_mul_f32 v[86:87], v[86:87], v[150:151]
	v_lshlrev_b32_e32 v148, 16, v230
	v_and_b32_e32 v149, 0xffff0000, v230
	v_pk_mul_f32 v[80:81], v[80:81], v[148:149]
	v_lshlrev_b32_e32 v150, 16, v231
	v_and_b32_e32 v151, 0xffff0000, v231
	v_pk_mul_f32 v[82:83], v[82:83], v[150:151]
	s_waitcnt vmcnt(3)
	v_lshlrev_b32_e32 v148, 16, v232
	v_and_b32_e32 v149, 0xffff0000, v232
	v_pk_mul_f32 v[60:61], v[60:61], v[148:149]
	v_lshlrev_b32_e32 v150, 16, v233
	v_and_b32_e32 v151, 0xffff0000, v233
	v_pk_mul_f32 v[62:63], v[62:63], v[150:151]
	v_lshlrev_b32_e32 v148, 16, v234
	v_and_b32_e32 v149, 0xffff0000, v234
	v_pk_mul_f32 v[56:57], v[56:57], v[148:149]
	v_lshlrev_b32_e32 v150, 16, v235
	v_and_b32_e32 v151, 0xffff0000, v235
	v_pk_mul_f32 v[58:59], v[58:59], v[150:151]
	s_waitcnt vmcnt(2)
	v_lshlrev_b32_e32 v148, 16, v236
	v_and_b32_e32 v149, 0xffff0000, v236
	v_pk_mul_f32 v[36:37], v[36:37], v[148:149]
	v_lshlrev_b32_e32 v150, 16, v237
	v_and_b32_e32 v151, 0xffff0000, v237
	v_pk_mul_f32 v[38:39], v[38:39], v[150:151]
	v_lshlrev_b32_e32 v148, 16, v238
	v_and_b32_e32 v149, 0xffff0000, v238
	v_pk_mul_f32 v[32:33], v[32:33], v[148:149]
	v_lshlrev_b32_e32 v150, 16, v239
	v_and_b32_e32 v151, 0xffff0000, v239
	v_pk_mul_f32 v[34:35], v[34:35], v[150:151]
	s_waitcnt vmcnt(1)
	v_lshlrev_b32_e32 v148, 16, v240
	v_and_b32_e32 v149, 0xffff0000, v240
	v_pk_mul_f32 v[20:21], v[20:21], v[148:149]
	v_lshlrev_b32_e32 v150, 16, v241
	v_and_b32_e32 v151, 0xffff0000, v241
	v_pk_mul_f32 v[22:23], v[22:23], v[150:151]
	v_lshlrev_b32_e32 v148, 16, v242
	v_and_b32_e32 v149, 0xffff0000, v242
	v_pk_mul_f32 v[16:17], v[16:17], v[148:149]
	v_lshlrev_b32_e32 v150, 16, v243
	v_and_b32_e32 v151, 0xffff0000, v243
	v_pk_mul_f32 v[18:19], v[18:19], v[150:151]
	s_waitcnt vmcnt(0)
	v_lshlrev_b32_e32 v148, 16, v244
	v_and_b32_e32 v149, 0xffff0000, v244
	v_pk_mul_f32 v[4:5], v[4:5], v[148:149]
	v_lshlrev_b32_e32 v150, 16, v245
	v_and_b32_e32 v151, 0xffff0000, v245
	v_pk_mul_f32 v[6:7], v[6:7], v[150:151]
	v_lshlrev_b32_e32 v148, 16, v246
	v_and_b32_e32 v149, 0xffff0000, v246
	v_pk_mul_f32 v[0:1], v[0:1], v[148:149]
	v_lshlrev_b32_e32 v150, 16, v247
	v_and_b32_e32 v151, 0xffff0000, v247
	v_pk_mul_f32 v[2:3], v[2:3], v[150:151]
	v_mov_b64_e32 v[148:149], s[6:7]
	v_cmp_ge_i64_e32 vcc, s[56:57], v[148:149]
	v_cmp_lt_i64_e64 s[0:1], s[56:57], v[148:149]
	s_cbranch_vccnz .LBB0_704
	s_ashr_i32 s9, s56, 31
	s_lshr_b32 s9, s9, 29
	s_add_i32 s9, s56, s9
	s_ashr_i32 s10, s9, 3
	s_and_b32 s9, s9, -8
	s_sub_i32 s9, s56, s9
	s_cmp_lt_i32 s9, 0
	s_cselect_b32 s34, s33, 0x44
	s_mul_i32 s9, s9, s34
	s_add_i32 s9, s9, s10
	s_ashr_i32 s10, s9, 31
	s_lshr_b32 s10, s10, 26
	s_add_i32 s10, s9, s10
	s_ashr_i32 s34, s10, 6
	s_lshl_b32 s34, s34, 3
	s_sub_i32 s35, 0x44, s34
	s_min_i32 s35, s35, 8
	s_abs_i32 s56, s35
	v_cvt_f32_u32_e32 v136, s56
	s_sub_i32 s58, 0, s56
	s_andn2_b32 s10, s10, 63
	s_sub_i32 s9, s9, s10
	v_rcp_iflag_f32_e32 v136, v136
	s_abs_i32 s10, s9
	s_xor_b32 s57, s9, s35
	s_ashr_i32 s57, s57, 31
	v_mul_f32_e32 v136, 0x4f7ffffe, v136
	v_cvt_u32_f32_e32 v136, v136
	s_nop 0
	v_readfirstlane_b32 s59, v136
	s_mul_i32 s58, s58, s59
	s_mul_hi_u32 s58, s59, s58
	s_add_i32 s59, s59, s58
	s_mul_hi_u32 s58, s10, s59
	s_mul_i32 s59, s58, s56
	s_sub_i32 s10, s10, s59
	s_add_i32 s60, s58, 1
	s_sub_i32 s59, s10, s56
	s_cmp_ge_u32 s10, s56
	s_cselect_b32 s58, s60, s58
	s_cselect_b32 s10, s59, s10
	s_add_i32 s59, s58, 1
	s_cmp_ge_u32 s10, s56
	s_cselect_b32 s10, s59, s58
	s_xor_b32 s10, s10, s57
	s_sub_i32 s10, s10, s57
	s_mul_i32 s35, s10, s35
	s_sub_i32 s9, s9, s35
	s_add_i32 s9, s34, s9
; template <class Epi>
; __device__ __forceinline__ void gemm_phase(LAS unsigned char* lds, const Gemm g, const StaticOrder& S, const Epi& E) {
;     ...
;         const bool has_next = S.next(ui + 1, nxt);
;         const char* nA = has_next ? (const char*)g.A + (size_t)nxt.pm * tstepA : cA; const char* nB = has_next ? (const char*)g.Bt + (size_t)nxt.pn * tstepB : cB;
;         PG8_KLOOP(cA, cB, nA, nB)
.LBB0_704:
	s_ashr_i32 s61, s8, 31
	s_mov_b32 s60, s8
	s_mov_b32 s8, s9
	s_ashr_i32 s9, s9, 31
	s_lshl_b64 s[34:35], s[8:9], 20
	s_add_u32 s58, s30, s34
	s_addc_u32 s59, s31, s35
	s_and_b64 s[34:35], s[0:1], exec
	s_cselect_b32 s9, s59, s79
	s_cselect_b32 s34, s58, s11
	s_ashr_i32 s11, s10, 31
	s_lshl_b64 s[56:57], s[10:11], 20
	v_readlane_b32 s84, v250, 5
	v_readlane_b32 s85, v250, 6
	s_add_u32 s56, s84, s56
	s_addc_u32 s57, s85, s57
	s_and_b64 s[84:85], s[0:1], exec
	s_cselect_b32 s11, s57, s63
	s_cselect_b32 s35, s56, s62
	s_add_u32 s79, s52, 0x900
	s_addc_u32 s84, s53, 0
	s_add_u32 s50, s50, 0x80880
	s_addc_u32 s51, s51, 0
	s_mov_b32 s85, -2
	v_readfirstlane_b32 s32, v179
	s_nop 0
	s_lshr_b32 s32, s32, 8
	s_cmp_eq_u32 s32, 0
	s_cselect_b64 vcc, -1, 0
.LBB0_705:
	ds_read_b128 v[148:151], v144
	ds_read_b128 v[152:155], v144 offset:1024
	ds_read_b128 v[156:159], v144 offset:2048
	ds_read_b128 v[160:163], v144 offset:3072
	ds_read_b128 v[164:167], v145
	ds_read_b128 v[168:171], v145 offset:1024
	ds_read_b128 v[172:175], v145 offset:2048
	ds_read_b128 v[180:183], v145 offset:3072
	s_add_u32 s52, s50, 0xfff80080
	s_addc_u32 s53, s51, -1
	s_cmp_eq_u32 s85, 12
	s_cselect_b32 s63, s9, s53
	s_cselect_b32 s62, s34, s52
	s_cselect_b32 s53, s11, s84
	s_cselect_b32 s52, s35, s79
	s_mov_b32 m0, s66
	v_lshl_add_u64 v[216:217], s[50:51], 0, v[128:129]
	ds_read_b128 v[184:187], v146
	ds_read_b128 v[188:191], v146 offset:1024
	ds_read_b128 v[192:195], v146 offset:2048
	ds_read_b128 v[196:199], v146 offset:3072
	ds_read_b128 v[200:203], v146 offset:4096
	ds_read_b128 v[204:207], v146 offset:5120
	ds_read_b128 v[208:211], v146 offset:6144
	ds_read_b128 v[212:215], v146 offset:7168
	global_load_lds_dwordx4 v[216:217], off
	v_lshl_add_u64 v[216:217], s[50:51], 0, v[132:133]
	s_mov_b32 m0, s67
	s_nop 0
	global_load_lds_dwordx4 v[216:217], off
	s_cbranch_vccnz .Lkw_skip_705_0
	s_waitcnt vmcnt(8)

.Lkw_post_705_0:
	s_barrier
	s_mov_b32 m0, s72
	v_lshl_add_u64 v[216:217], s[52:53], 0, v[130:131]
	s_add_u32 s86, s52, 0x80000
	ds_read_b128 v[184:187], v146 offset:16384
	ds_read_b128 v[188:191], v146 offset:17408
	ds_read_b128 v[192:195], v146 offset:18432
	ds_read_b128 v[196:199], v146 offset:19456
	ds_read_b128 v[200:203], v146 offset:20480
	ds_read_b128 v[204:207], v146 offset:21504
	ds_read_b128 v[208:211], v146 offset:22528
	ds_read_b128 v[212:215], v146 offset:23552
	global_load_lds_dwordx4 v[216:217], off
	v_lshl_add_u64 v[218:219], s[52:53], 0, v[134:135]
	s_mov_b32 m0, s73
	s_addc_u32 s87, s53, 0
	global_load_lds_dwordx4 v[218:219], off
	v_lshl_add_u64 v[222:223], s[86:87], 0, v[130:131]
	s_mov_b32 m0, s74
	v_lshl_add_u64 v[224:225], s[62:63], 0, v[132:133]
	global_load_lds_dwordx4 v[222:223], off
	v_lshl_add_u64 v[222:223], s[86:87], 0, v[134:135]
	s_mov_b32 m0, s76
	s_nop 0
	global_load_lds_dwordx4 v[222:223], off
	v_lshl_add_u64 v[222:223], s[62:63], 0, v[128:129]
	s_mov_b32 m0, s36
	s_nop 0
	global_load_lds_dwordx4 v[222:223], off
	s_mov_b32 m0, s37
	s_nop 0
	global_load_lds_dwordx4 v[224:225], off
	s_cbranch_vccnz .Lkw_skip_705_1
	s_waitcnt vmcnt(8)

.Lkw_post_705_1:
	s_barrier
	ds_read_b128 v[148:151], v147
	ds_read_b128 v[152:155], v147 offset:1024
	ds_read_b128 v[156:159], v147 offset:2048
	ds_read_b128 v[160:163], v147 offset:3072
	ds_read_b128 v[164:167], v138
	ds_read_b128 v[168:171], v138 offset:1024
	ds_read_b128 v[172:175], v138 offset:2048
	ds_read_b128 v[180:183], v138 offset:3072
	s_add_u32 s62, s62, 0x80000
	s_addc_u32 s63, s63, 0
	s_mov_b32 m0, s40
	v_lshl_add_u64 v[226:227], s[62:63], 0, v[128:129]
	ds_read_b128 v[184:187], v146 offset:32768
	ds_read_b128 v[188:191], v146 offset:33792
	ds_read_b128 v[192:195], v146 offset:34816
	ds_read_b128 v[196:199], v146 offset:35840
	ds_read_b128 v[200:203], v146 offset:36864
	ds_read_b128 v[204:207], v146 offset:37888
	ds_read_b128 v[208:211], v146 offset:38912
	ds_read_b128 v[212:215], v146 offset:39936
	global_load_lds_dwordx4 v[226:227], off
	v_lshl_add_u64 v[226:227], s[62:63], 0, v[132:133]
	s_mov_b32 m0, s41
	s_nop 0
	global_load_lds_dwordx4 v[226:227], off
	s_cbranch_vccnz .Lkw_skip_705_2
	s_waitcnt vmcnt(8)

.Lkw_post_705_2:
	s_barrier
	s_mov_b32 m0, s80
	v_lshl_add_u64 v[216:217], v[216:217], 0, s[22:23]
	s_add_u32 s52, s52, 0x80080
	ds_read_b128 v[184:187], v146 offset:49152
	ds_read_b128 v[188:191], v146 offset:50176
	ds_read_b128 v[192:195], v146 offset:51200
	ds_read_b128 v[196:199], v146 offset:52224
	ds_read_b128 v[200:203], v146 offset:53248
	ds_read_b128 v[204:207], v146 offset:54272
	ds_read_b128 v[208:211], v146 offset:55296
	ds_read_b128 v[212:215], v146 offset:56320
	global_load_lds_dwordx4 v[216:217], off
	v_lshl_add_u64 v[216:217], v[218:219], 0, s[22:23]
	s_mov_b32 m0, s81
	s_addc_u32 s53, s53, 0
	global_load_lds_dwordx4 v[216:217], off
	v_lshl_add_u64 v[216:217], s[52:53], 0, v[130:131]
	s_mov_b32 m0, s82
	s_nop 0
	global_load_lds_dwordx4 v[216:217], off
	v_lshl_add_u64 v[216:217], s[52:53], 0, v[134:135]
	s_mov_b32 m0, s83
	s_nop 0
	global_load_lds_dwordx4 v[216:217], off
	v_lshl_add_u64 v[216:217], v[222:223], 0, s[22:23]
	s_mov_b32 m0, s43
	s_nop 0
	global_load_lds_dwordx4 v[216:217], off
	v_lshl_add_u64 v[216:217], v[224:225], 0, s[22:23]
	s_mov_b32 m0, s64
	s_nop 0
	global_load_lds_dwordx4 v[216:217], off
	s_cbranch_vccnz .Lkw_skip_705_3
	s_waitcnt vmcnt(8)

; #define PG8_BAR __builtin_amdgcn_s_barrier()
; template <class Epi>
; __device__ __forceinline__ void gemm_phase(LAS unsigned char* lds, const Gemm g, const StaticOrder& S, const Epi& E) {
;     ...
;     for (;;) {
;         if constexpr (Epi::NPART == 2) {
;             const char* mA = cA + (size_t)K * 2; const char* mB = cB + (size_t)K * 2;
;             PG8_KLOOP(cA, cB, mA, mB)
;             E.mid(acc, cur, wr, wc, fr, fq);
;             cA = mA; cB = mB;
;         }
;         const bool has_next = S.next(ui + 1, nxt);
;         const char* nA = has_next ? (const char*)g.A + (size_t)nxt.pm * tstepA : cA; const char* nB = has_next ? (const char*)g.Bt + (size_t)nxt.pn * tstepB : cB;
;         PG8_KLOOP(cA, cB, nA, nB)
;         if (wr == 0) PG8_BAR;
.Lkw_post_705_3:
	s_barrier
	s_add_i32 s85, s85, 2
	s_add_u32 s79, s79, 0x100
	s_addc_u32 s84, s84, 0
	s_add_u32 s50, s50, 0x100
	s_addc_u32 s51, s51, 0
	s_cmp_gt_u32 s85, 13
	s_cbranch_scc0 .LBB0_705
	s_and_b64 vcc, exec, s[26:27]
	s_cbranch_vccz .LBB0_708
	s_barrier

; template <class Epi>
; __device__ __forceinline__ void gemm_phase(LAS unsigned char* lds, const Gemm g, const StaticOrder& S, const Epi& E) {
;     ...
;         for (int a = 0; a < 2; ++a)
; #pragma unroll
;             for (int b = 0; b < 2; ++b)
; #pragma unroll
;                 for (int m = 0; m < 4; ++m)
; #pragma unroll
;                     for (int n = 0; n < 2; ++n) acc[a][b][m][n] = (f32x4){0.f, 0.f, 0.f, 0.f};
;         cur = nxt; cA = nA; cB = nB; ++ui;
.LBB0_806:
	s_ashr_i32 s51, s50, 31
	s_lshl_b64 s[34:35], s[50:51], 20
	s_add_u32 s52, s18, s34
	s_addc_u32 s53, s19, s35
	s_and_b64 s[34:35], s[0:1], exec
	s_cselect_b32 s51, s53, s61
	s_cselect_b32 s57, s52, s60
	s_ashr_i32 s49, s48, 31
	s_lshl_b64 s[34:35], s[48:49], 20
	s_add_u32 s54, s94, s34
	s_addc_u32 s55, s95, s35
	s_and_b64 s[34:35], s[0:1], exec
	s_cselect_b32 s49, s55, s63
	s_cselect_b32 s67, s54, s62
	s_add_u32 s60, s60, 0x80080
	s_addc_u32 s61, s61, 0
	s_add_u32 s72, s62, 0x100
	v_mov_b32_e32 v0, 0
	s_addc_u32 s73, s63, 0
	s_mov_b32 s74, -2
	s_waitcnt lgkmcnt(0)
	v_mov_b32_e32 v1, v0
	v_mov_b32_e32 v2, v0
	v_mov_b32_e32 v3, v0
	v_mov_b32_e32 v4, v0
	v_mov_b32_e32 v5, v0
	v_mov_b32_e32 v6, v0
	v_mov_b32_e32 v7, v0
	v_mov_b32_e32 v16, v0
	v_mov_b32_e32 v17, v0
	v_mov_b32_e32 v18, v0
	v_mov_b32_e32 v19, v0
	v_mov_b32_e32 v20, v0
	v_mov_b32_e32 v21, v0
	v_mov_b32_e32 v22, v0
	v_mov_b32_e32 v23, v0
	v_mov_b32_e32 v32, v0
	v_mov_b32_e32 v33, v0
	v_mov_b32_e32 v34, v0
	v_mov_b32_e32 v35, v0
	v_mov_b32_e32 v36, v0
	v_mov_b32_e32 v37, v0
	v_mov_b32_e32 v38, v0
	v_mov_b32_e32 v39, v0
	v_mov_b32_e32 v48, v0
	v_mov_b32_e32 v49, v0
	v_mov_b32_e32 v50, v0
	v_mov_b32_e32 v51, v0
	v_mov_b32_e32 v52, v0
	v_mov_b32_e32 v53, v0
	v_mov_b32_e32 v54, v0
	v_mov_b32_e32 v55, v0
	v_mov_b32_e32 v8, v0
	v_mov_b32_e32 v9, v0
	v_mov_b32_e32 v10, v0
	v_mov_b32_e32 v11, v0
	v_mov_b32_e32 v12, v0
	v_mov_b32_e32 v13, v0
	v_mov_b32_e32 v14, v0
	v_mov_b32_e32 v15, v0
	v_mov_b32_e32 v24, v0
	v_mov_b32_e32 v25, v0
	v_mov_b32_e32 v26, v0
	v_mov_b32_e32 v27, v0
	v_mov_b32_e32 v28, v0
	v_mov_b32_e32 v29, v0
	v_mov_b32_e32 v30, v0
	v_mov_b32_e32 v31, v0
	v_mov_b32_e32 v40, v0
	v_mov_b32_e32 v41, v0
	v_mov_b32_e32 v42, v0
	v_mov_b32_e32 v43, v0
	v_mov_b32_e32 v44, v0
	v_mov_b32_e32 v45, v0
	v_mov_b32_e32 v46, v0
	v_mov_b32_e32 v47, v0
	v_mov_b32_e32 v56, v0
	v_mov_b32_e32 v57, v0
	v_mov_b32_e32 v58, v0
	v_mov_b32_e32 v59, v0
	v_mov_b32_e32 v60, v0
	v_mov_b32_e32 v61, v0
	v_mov_b32_e32 v62, v0
	v_mov_b32_e32 v63, v0
	v_mov_b32_e32 v64, v0
	v_mov_b32_e32 v65, v0
	v_mov_b32_e32 v66, v0
	v_mov_b32_e32 v67, v0
	v_mov_b32_e32 v68, v0
	v_mov_b32_e32 v69, v0
	v_mov_b32_e32 v70, v0
	v_mov_b32_e32 v71, v0
	v_mov_b32_e32 v80, v0
	v_mov_b32_e32 v81, v0
	v_mov_b32_e32 v82, v0
	v_mov_b32_e32 v83, v0
	v_mov_b32_e32 v84, v0
	v_mov_b32_e32 v85, v0
	v_mov_b32_e32 v86, v0
	v_mov_b32_e32 v87, v0
	v_mov_b32_e32 v96, v0
	v_mov_b32_e32 v97, v0
	v_mov_b32_e32 v98, v0
	v_mov_b32_e32 v99, v0
	v_mov_b32_e32 v100, v0
	v_mov_b32_e32 v101, v0
	v_mov_b32_e32 v102, v0
	v_mov_b32_e32 v103, v0
	v_mov_b32_e32 v112, v0
	v_mov_b32_e32 v113, v0
	v_mov_b32_e32 v114, v0
	v_mov_b32_e32 v115, v0
	v_mov_b32_e32 v116, v0
	v_mov_b32_e32 v117, v0
	v_mov_b32_e32 v118, v0
	v_mov_b32_e32 v119, v0
	v_mov_b32_e32 v72, v0
	v_mov_b32_e32 v73, v0
	v_mov_b32_e32 v74, v0
	v_mov_b32_e32 v75, v0
	v_mov_b32_e32 v76, v0
	v_mov_b32_e32 v77, v0
	v_mov_b32_e32 v78, v0
	v_mov_b32_e32 v79, v0
	v_mov_b32_e32 v88, v0
	v_mov_b32_e32 v89, v0
	v_mov_b32_e32 v90, v0
	v_mov_b32_e32 v91, v0
	v_mov_b32_e32 v92, v0
	v_mov_b32_e32 v93, v0
	v_mov_b32_e32 v94, v0
	v_mov_b32_e32 v95, v0
	v_mov_b32_e32 v104, v0
	v_mov_b32_e32 v105, v0
	v_mov_b32_e32 v106, v0
	v_mov_b32_e32 v107, v0
	v_mov_b32_e32 v108, v0
	v_mov_b32_e32 v109, v0
	v_mov_b32_e32 v110, v0
	v_mov_b32_e32 v111, v0
	v_mov_b32_e32 v120, v0
	v_mov_b32_e32 v121, v0
	v_mov_b32_e32 v122, v0
	v_mov_b32_e32 v123, v0
	v_mov_b32_e32 v124, v0
	v_mov_b32_e32 v125, v0
	v_mov_b32_e32 v126, v0
	v_mov_b32_e32 v127, v0
	v_readfirstlane_b32 s32, v179
	s_nop 0
	s_lshr_b32 s32, s32, 8
	s_cmp_eq_u32 s32, 0
	s_cselect_b64 vcc, -1, 0
.LBB0_807:
	ds_read_b128 v[138:141], v148
	ds_read_b128 v[152:155], v148 offset:1024
	ds_read_b128 v[156:159], v148 offset:2048
	ds_read_b128 v[160:163], v148 offset:3072
	ds_read_b128 v[164:167], v149
	ds_read_b128 v[168:171], v149 offset:1024
	ds_read_b128 v[172:175], v149 offset:2048
	ds_read_b128 v[180:183], v149 offset:3072
	s_add_u32 s34, s60, 0xfff80080
	s_addc_u32 s35, s61, -1
	s_cmp_eq_u32 s74, 28
	s_cselect_b32 s65, s51, s35
	s_cselect_b32 s64, s57, s34
	s_cselect_b32 s63, s49, s73
	s_cselect_b32 s62, s67, s72
	v_lshl_add_u64 v[216:217], s[60:61], 0, v[128:129]
	s_add_i32 m0, s15, 0xc000
	ds_read_b128 v[184:187], v150
	ds_read_b128 v[188:191], v150 offset:1024
	ds_read_b128 v[192:195], v150 offset:2048
	ds_read_b128 v[196:199], v150 offset:3072
	ds_read_b128 v[200:203], v150 offset:4096
	ds_read_b128 v[204:207], v150 offset:5120
	ds_read_b128 v[208:211], v150 offset:6144
	ds_read_b128 v[212:215], v150 offset:7168
	global_load_lds_dwordx4 v[216:217], off
	v_lshl_add_u64 v[216:217], s[60:61], 0, v[132:133]
	s_add_i32 m0, s15, 0xe000
	s_nop 0
	global_load_lds_dwordx4 v[216:217], off
	s_cbranch_vccnz .Lkw_skip_807_0
	s_waitcnt vmcnt(8)
.Lkw_skip_807_0:
	s_waitcnt lgkmcnt(0)
	s_barrier
	s_setprio 1
	s_waitcnt lgkmcnt(0)
	v_mfma_f32_16x16x32_bf16 v[124:127], v[138:141], v[184:187], v[124:127]
	v_mfma_f32_16x16x32_bf16 v[120:123], v[156:159], v[184:187], v[120:123]
	v_mfma_f32_16x16x32_bf16 v[108:111], v[138:141], v[192:195], v[108:111]
	v_mfma_f32_16x16x32_bf16 v[104:107], v[156:159], v[192:195], v[104:107]
	v_mfma_f32_16x16x32_bf16 v[92:95], v[138:141], v[200:203], v[92:95]
	v_mfma_f32_16x16x32_bf16 v[88:91], v[156:159], v[200:203], v[88:91]
	v_mfma_f32_16x16x32_bf16 v[76:79], v[138:141], v[208:211], v[76:79]
	v_mfma_f32_16x16x32_bf16 v[72:75], v[156:159], v[208:211], v[72:75]
	v_mfma_f32_16x16x32_bf16 v[124:127], v[152:155], v[188:191], v[124:127]
	v_mfma_f32_16x16x32_bf16 v[120:123], v[160:163], v[188:191], v[120:123]
	v_mfma_f32_16x16x32_bf16 v[108:111], v[152:155], v[196:199], v[108:111]
	v_mfma_f32_16x16x32_bf16 v[104:107], v[160:163], v[196:199], v[104:107]
	v_mfma_f32_16x16x32_bf16 v[92:95], v[152:155], v[204:207], v[92:95]
	v_mfma_f32_16x16x32_bf16 v[88:91], v[160:163], v[204:207], v[88:91]
	v_mfma_f32_16x16x32_bf16 v[76:79], v[152:155], v[212:215], v[76:79]
	v_mfma_f32_16x16x32_bf16 v[72:75], v[160:163], v[212:215], v[72:75]
	s_setprio 0
	s_setprio 1
	v_mfma_f32_16x16x32_bf16 v[116:119], v[164:167], v[184:187], v[116:119]
	v_mfma_f32_16x16x32_bf16 v[112:115], v[172:175], v[184:187], v[112:115]
	v_mfma_f32_16x16x32_bf16 v[100:103], v[164:167], v[192:195], v[100:103]
	v_mfma_f32_16x16x32_bf16 v[96:99], v[172:175], v[192:195], v[96:99]
	v_mfma_f32_16x16x32_bf16 v[84:87], v[164:167], v[200:203], v[84:87]
	v_mfma_f32_16x16x32_bf16 v[80:83], v[172:175], v[200:203], v[80:83]
	v_mfma_f32_16x16x32_bf16 v[68:71], v[164:167], v[208:211], v[68:71]
	v_mfma_f32_16x16x32_bf16 v[64:67], v[172:175], v[208:211], v[64:67]
	v_mfma_f32_16x16x32_bf16 v[116:119], v[168:171], v[188:191], v[116:119]
	v_mfma_f32_16x16x32_bf16 v[112:115], v[180:183], v[188:191], v[112:115]
	v_mfma_f32_16x16x32_bf16 v[100:103], v[168:171], v[196:199], v[100:103]
	v_mfma_f32_16x16x32_bf16 v[96:99], v[180:183], v[196:199], v[96:99]
	v_mfma_f32_16x16x32_bf16 v[84:87], v[168:171], v[204:207], v[84:87]
	v_mfma_f32_16x16x32_bf16 v[80:83], v[180:183], v[204:207], v[80:83]
	v_mfma_f32_16x16x32_bf16 v[68:71], v[168:171], v[212:215], v[68:71]
	v_mfma_f32_16x16x32_bf16 v[64:67], v[180:183], v[212:215], v[64:67]
	s_setprio 0
	s_cbranch_vccz .Lkw_post_807_0
	s_waitcnt vmcnt(8)
.Lkw_post_807_0:
	s_barrier
	s_add_i32 s34, s59, s14
	v_lshl_add_u64 v[216:217], s[62:63], 0, v[130:131]
	s_mov_b32 m0, s34
	ds_read_b128 v[184:187], v150 offset:16384
	ds_read_b128 v[188:191], v150 offset:17408
	ds_read_b128 v[192:195], v150 offset:18432
	ds_read_b128 v[196:199], v150 offset:19456
	ds_read_b128 v[200:203], v150 offset:20480
	ds_read_b128 v[204:207], v150 offset:21504
	ds_read_b128 v[208:211], v150 offset:22528
	ds_read_b128 v[212:215], v150 offset:23552
	global_load_lds_dwordx4 v[216:217], off
	s_add_i32 m0, s34, 0x2000
	s_add_u32 s34, s62, 0x80000
	v_lshl_add_u64 v[218:219], s[62:63], 0, v[134:135]
	s_addc_u32 s35, s63, 0
	s_add_i32 s75, s66, s14
	global_load_lds_dwordx4 v[218:219], off
	v_lshl_add_u64 v[222:223], s[34:35], 0, v[130:131]
	s_mov_b32 m0, s75
	v_lshl_add_u64 v[224:225], s[64:65], 0, v[132:133]
	global_load_lds_dwordx4 v[222:223], off
	v_lshl_add_u64 v[222:223], s[34:35], 0, v[134:135]
	s_add_i32 m0, s75, 0x2000
	s_nop 0
	global_load_lds_dwordx4 v[222:223], off
	v_lshl_add_u64 v[222:223], s[64:65], 0, v[128:129]
	s_mov_b32 m0, s15
	s_nop 0
	global_load_lds_dwordx4 v[222:223], off
	s_mov_b32 m0, s33
	s_nop 0
	global_load_lds_dwordx4 v[224:225], off
	s_cbranch_vccnz .Lkw_skip_807_1
	s_waitcnt vmcnt(8)
.Lkw_skip_807_1:
	s_waitcnt lgkmcnt(0)
	s_barrier
	s_setprio 1
	s_waitcnt lgkmcnt(0)
	v_mfma_f32_16x16x32_bf16 v[60:63], v[138:141], v[184:187], v[60:63]
	v_mfma_f32_16x16x32_bf16 v[56:59], v[156:159], v[184:187], v[56:59]
	v_mfma_f32_16x16x32_bf16 v[44:47], v[138:141], v[192:195], v[44:47]
	v_mfma_f32_16x16x32_bf16 v[40:43], v[156:159], v[192:195], v[40:43]
	v_mfma_f32_16x16x32_bf16 v[28:31], v[138:141], v[200:203], v[28:31]
	v_mfma_f32_16x16x32_bf16 v[24:27], v[156:159], v[200:203], v[24:27]
	v_mfma_f32_16x16x32_bf16 v[12:15], v[138:141], v[208:211], v[12:15]
	v_mfma_f32_16x16x32_bf16 v[8:11], v[156:159], v[208:211], v[8:11]
	v_mfma_f32_16x16x32_bf16 v[60:63], v[152:155], v[188:191], v[60:63]
	v_mfma_f32_16x16x32_bf16 v[56:59], v[160:163], v[188:191], v[56:59]
	v_mfma_f32_16x16x32_bf16 v[44:47], v[152:155], v[196:199], v[44:47]
	v_mfma_f32_16x16x32_bf16 v[40:43], v[160:163], v[196:199], v[40:43]
	v_mfma_f32_16x16x32_bf16 v[28:31], v[152:155], v[204:207], v[28:31]
	v_mfma_f32_16x16x32_bf16 v[24:27], v[160:163], v[204:207], v[24:27]
	v_mfma_f32_16x16x32_bf16 v[12:15], v[152:155], v[212:215], v[12:15]
	v_mfma_f32_16x16x32_bf16 v[8:11], v[160:163], v[212:215], v[8:11]
	s_setprio 0
	s_setprio 1
	v_mfma_f32_16x16x32_bf16 v[52:55], v[164:167], v[184:187], v[52:55]
	v_mfma_f32_16x16x32_bf16 v[48:51], v[172:175], v[184:187], v[48:51]
	v_mfma_f32_16x16x32_bf16 v[36:39], v[164:167], v[192:195], v[36:39]
	v_mfma_f32_16x16x32_bf16 v[32:35], v[172:175], v[192:195], v[32:35]
	v_mfma_f32_16x16x32_bf16 v[20:23], v[164:167], v[200:203], v[20:23]
	v_mfma_f32_16x16x32_bf16 v[16:19], v[172:175], v[200:203], v[16:19]
	v_mfma_f32_16x16x32_bf16 v[4:7], v[164:167], v[208:211], v[4:7]
	v_mfma_f32_16x16x32_bf16 v[0:3], v[172:175], v[208:211], v[0:3]
	v_mfma_f32_16x16x32_bf16 v[52:55], v[168:171], v[188:191], v[52:55]
	v_mfma_f32_16x16x32_bf16 v[48:51], v[180:183], v[188:191], v[48:51]
	v_mfma_f32_16x16x32_bf16 v[36:39], v[168:171], v[196:199], v[36:39]
	v_mfma_f32_16x16x32_bf16 v[32:35], v[180:183], v[196:199], v[32:35]
	v_mfma_f32_16x16x32_bf16 v[20:23], v[168:171], v[204:207], v[20:23]
	v_mfma_f32_16x16x32_bf16 v[16:19], v[180:183], v[204:207], v[16:19]
	v_mfma_f32_16x16x32_bf16 v[4:7], v[168:171], v[212:215], v[4:7]
	v_mfma_f32_16x16x32_bf16 v[0:3], v[180:183], v[212:215], v[0:3]
	s_setprio 0
	s_cbranch_vccz .Lkw_post_807_1
	s_waitcnt vmcnt(8)
.Lkw_post_807_1:
	s_barrier
	s_add_i32 s75, 0, 0x18000
	s_add_i32 s76, 0, 0x1c000
	v_add_u32_e32 v160, s75, v143
	v_add_u32_e32 v177, s76, v143
	ds_read_b128 v[138:141], v160
	ds_read_b128 v[152:155], v160 offset:1024
	ds_read_b128 v[156:159], v160 offset:2048
	ds_read_b128 v[160:163], v160 offset:3072
	ds_read_b128 v[164:167], v177
	ds_read_b128 v[168:171], v177 offset:1024
	ds_read_b128 v[172:175], v177 offset:2048
	ds_read_b128 v[180:183], v177 offset:3072
	s_add_u32 s34, s64, 0x80000
	s_addc_u32 s35, s65, 0
	s_mov_b32 m0, s36
	v_lshl_add_u64 v[226:227], s[34:35], 0, v[128:129]
	ds_read_b128 v[184:187], v150 offset:32768
	ds_read_b128 v[188:191], v150 offset:33792
	ds_read_b128 v[192:195], v150 offset:34816
	ds_read_b128 v[196:199], v150 offset:35840
	ds_read_b128 v[200:203], v150 offset:36864
	ds_read_b128 v[204:207], v150 offset:37888
	ds_read_b128 v[208:211], v150 offset:38912
	ds_read_b128 v[212:215], v150 offset:39936
	global_load_lds_dwordx4 v[226:227], off
	v_lshl_add_u64 v[226:227], s[34:35], 0, v[132:133]
	s_mov_b32 m0, s37
	s_nop 0
	global_load_lds_dwordx4 v[226:227], off
	s_cbranch_vccnz .Lkw_skip_807_2
	s_waitcnt vmcnt(8)

.Lkw_post_807_2:
	s_barrier
	s_add_i32 s34, s75, s14
	v_lshl_add_u64 v[216:217], v[216:217], 0, s[20:21]
	s_mov_b32 m0, s34
	ds_read_b128 v[184:187], v150 offset:49152
	ds_read_b128 v[188:191], v150 offset:50176
	ds_read_b128 v[192:195], v150 offset:51200
	ds_read_b128 v[196:199], v150 offset:52224
	ds_read_b128 v[200:203], v150 offset:53248
	ds_read_b128 v[204:207], v150 offset:54272
	ds_read_b128 v[208:211], v150 offset:55296
	ds_read_b128 v[212:215], v150 offset:56320
	global_load_lds_dwordx4 v[216:217], off
	s_add_i32 m0, s34, 0x2000
	s_add_u32 s34, s62, 0x80080
	v_lshl_add_u64 v[216:217], v[218:219], 0, s[20:21]
	s_addc_u32 s35, s63, 0
	s_add_i32 s62, s76, s14
	global_load_lds_dwordx4 v[216:217], off
	v_lshl_add_u64 v[216:217], s[34:35], 0, v[130:131]
	s_mov_b32 m0, s62
	s_nop 0
	global_load_lds_dwordx4 v[216:217], off
	v_lshl_add_u64 v[216:217], s[34:35], 0, v[134:135]
	s_add_i32 m0, s62, 0x2000
	s_nop 0
	global_load_lds_dwordx4 v[216:217], off
	v_lshl_add_u64 v[216:217], v[222:223], 0, s[20:21]
	s_mov_b32 m0, s40
	s_nop 0
	global_load_lds_dwordx4 v[216:217], off
	v_lshl_add_u64 v[216:217], v[224:225], 0, s[20:21]
	s_mov_b32 m0, s41
	s_nop 0
	global_load_lds_dwordx4 v[216:217], off
	s_cbranch_vccnz .Lkw_skip_807_3
	s_waitcnt vmcnt(8)

; #define PG8_BAR __builtin_amdgcn_s_barrier()
; template <class Epi>
; __device__ __forceinline__ void gemm_phase(LAS unsigned char* lds, const Gemm g, const StaticOrder& S, const Epi& E) {
;     ...
;     for (;;) {
;         if constexpr (Epi::NPART == 2) {
;             const char* mA = cA + (size_t)K * 2; const char* mB = cB + (size_t)K * 2;
;             PG8_KLOOP(cA, cB, mA, mB)
;             E.mid(acc, cur, wr, wc, fr, fq);
;             cA = mA; cB = mB;
;         }
;         const bool has_next = S.next(ui + 1, nxt);
;         const char* nA = has_next ? (const char*)g.A + (size_t)nxt.pm * tstepA : cA; const char* nB = has_next ? (const char*)g.Bt + (size_t)nxt.pn * tstepB : cB;
;         PG8_KLOOP(cA, cB, nA, nB)
;         if (wr == 0) PG8_BAR;
.Lkw_post_807_3:
	s_barrier
	s_add_i32 s74, s74, 2
	s_add_u32 s60, s60, 0x100
	s_addc_u32 s61, s61, 0
	s_add_u32 s72, s72, 0x100
	s_addc_u32 s73, s73, 0
	s_cmp_gt_u32 s74, 29
	s_cbranch_scc0 .LBB0_807
	s_and_b64 vcc, exec, s[26:27]
	s_cbranch_vccz .LBB0_810
	s_barrier

; template <class Epi>
; __device__ __forceinline__ void gemm_phase(LAS unsigned char* lds, const Gemm g, const StaticOrder& S, const Epi& E) {
;     ...
;         for (int a = 0; a < 2; ++a)
; #pragma unroll
;             for (int b = 0; b < 2; ++b)
; #pragma unroll
;                 for (int m = 0; m < 4; ++m)
; #pragma unroll
;                     for (int n = 0; n < 2; ++n) acc[a][b][m][n] = (f32x4){0.f, 0.f, 0.f, 0.f};
;         cur = nxt; cA = nA; cB = nB; ++ui;
.LBB0_895:
	s_ashr_i32 s67, s66, 31
	s_lshl_b64 s[34:35], s[66:67], 20
	s_add_u32 s80, s16, s34
	s_addc_u32 s81, s17, s35
	s_and_b64 s[34:35], s[6:7], exec
	s_cselect_b32 s1, s81, s11
	s_cselect_b32 s9, s80, s10
	s_ashr_i32 s65, s64, 31
	s_lshl_b64 s[34:35], s[64:65], 20
	s_add_u32 s82, s44, s34
	s_addc_u32 s83, s45, s35
	s_and_b64 s[34:35], s[6:7], exec
	s_cselect_b32 s41, s83, s75
	s_cselect_b32 s65, s82, s74
	s_add_u32 s10, s10, 0x80080
	s_addc_u32 s11, s11, 0
	s_add_u32 s67, s74, 0x100
	v_mov_b32_e32 v24, 0
	s_addc_u32 s72, s75, 0
	s_mov_b32 s73, -2
	v_mov_b32_e32 v25, v24
	v_mov_b32_e32 v26, v24
	v_mov_b32_e32 v27, v24
	v_mov_b32_e32 v72, v24
	v_mov_b32_e32 v73, v24
	v_mov_b32_e32 v74, v24
	v_mov_b32_e32 v75, v24
	v_mov_b32_e32 v0, v24
	v_mov_b32_e32 v1, v24
	v_mov_b32_e32 v2, v24
	v_mov_b32_e32 v3, v24
	v_mov_b32_e32 v32, v24
	v_mov_b32_e32 v33, v24
	v_mov_b32_e32 v34, v24
	v_mov_b32_e32 v35, v24
	v_mov_b32_e32 v4, v24
	v_mov_b32_e32 v5, v24
	v_mov_b32_e32 v6, v24
	v_mov_b32_e32 v7, v24
	v_mov_b32_e32 v40, v24
	v_mov_b32_e32 v41, v24
	v_mov_b32_e32 v42, v24
	v_mov_b32_e32 v43, v24
	v_mov_b32_e32 v8, v24
	v_mov_b32_e32 v9, v24
	v_mov_b32_e32 v10, v24
	v_mov_b32_e32 v11, v24
	v_mov_b32_e32 v48, v24
	v_mov_b32_e32 v49, v24
	v_mov_b32_e32 v50, v24
	v_mov_b32_e32 v51, v24
	v_mov_b32_e32 v28, v24
	v_mov_b32_e32 v29, v24
	v_mov_b32_e32 v30, v24
	v_mov_b32_e32 v31, v24
	v_mov_b32_e32 v76, v24
	v_mov_b32_e32 v77, v24
	v_mov_b32_e32 v78, v24
	v_mov_b32_e32 v79, v24
	v_mov_b32_e32 v12, v24
	v_mov_b32_e32 v13, v24
	v_mov_b32_e32 v14, v24
	v_mov_b32_e32 v15, v24
	v_mov_b32_e32 v36, v24
	v_mov_b32_e32 v37, v24
	v_mov_b32_e32 v38, v24
	v_mov_b32_e32 v39, v24
	v_mov_b32_e32 v16, v24
	v_mov_b32_e32 v17, v24
	v_mov_b32_e32 v18, v24
	v_mov_b32_e32 v19, v24
	v_mov_b32_e32 v44, v24
	v_mov_b32_e32 v45, v24
	v_mov_b32_e32 v46, v24
	v_mov_b32_e32 v47, v24
	v_mov_b32_e32 v20, v24
	v_mov_b32_e32 v21, v24
	v_mov_b32_e32 v22, v24
	v_mov_b32_e32 v23, v24
	v_mov_b32_e32 v52, v24
	v_mov_b32_e32 v53, v24
	v_mov_b32_e32 v54, v24
	v_mov_b32_e32 v55, v24
	v_mov_b32_e32 v80, v24
	v_mov_b32_e32 v81, v24
	v_mov_b32_e32 v82, v24
	v_mov_b32_e32 v83, v24
	v_mov_b32_e32 v112, v24
	v_mov_b32_e32 v113, v24
	v_mov_b32_e32 v114, v24
	v_mov_b32_e32 v115, v24
	v_mov_b32_e32 v56, v24
	v_mov_b32_e32 v57, v24
	v_mov_b32_e32 v58, v24
	v_mov_b32_e32 v59, v24
	v_mov_b32_e32 v96, v24
	v_mov_b32_e32 v97, v24
	v_mov_b32_e32 v98, v24
	v_mov_b32_e32 v99, v24
	v_mov_b32_e32 v60, v24
	v_mov_b32_e32 v61, v24
	v_mov_b32_e32 v62, v24
	v_mov_b32_e32 v63, v24
	v_mov_b32_e32 v104, v24
	v_mov_b32_e32 v105, v24
	v_mov_b32_e32 v106, v24
	v_mov_b32_e32 v107, v24
	v_mov_b32_e32 v88, v24
	v_mov_b32_e32 v89, v24
	v_mov_b32_e32 v90, v24
	v_mov_b32_e32 v91, v24
	v_mov_b32_e32 v122, v24
	v_mov_b32_e32 v123, v24
	v_mov_b32_e32 v124, v24
	v_mov_b32_e32 v125, v24
	v_mov_b32_e32 v84, v24
	v_mov_b32_e32 v85, v24
	v_mov_b32_e32 v86, v24
	v_mov_b32_e32 v87, v24
	v_mov_b32_e32 v116, v24
	v_mov_b32_e32 v117, v24
	v_mov_b32_e32 v118, v24
	v_mov_b32_e32 v119, v24
	v_mov_b32_e32 v64, v24
	v_mov_b32_e32 v65, v24
	v_mov_b32_e32 v66, v24
	v_mov_b32_e32 v67, v24
	v_mov_b32_e32 v100, v24
	v_mov_b32_e32 v101, v24
	v_mov_b32_e32 v102, v24
	v_mov_b32_e32 v103, v24
	v_mov_b32_e32 v68, v24
	v_mov_b32_e32 v69, v24
	v_mov_b32_e32 v70, v24
	v_mov_b32_e32 v71, v24
	v_mov_b32_e32 v108, v24
	v_mov_b32_e32 v109, v24
	v_mov_b32_e32 v110, v24
	v_mov_b32_e32 v111, v24
	v_mov_b32_e32 v92, v24
	v_mov_b32_e32 v93, v24
	v_mov_b32_e32 v94, v24
	v_mov_b32_e32 v95, v24
	v_mov_b32_e32 v126, v24
	v_mov_b32_e32 v127, v24
	v_mov_b32_e32 v128, v24
	v_mov_b32_e32 v129, v24
	v_readfirstlane_b32 s32, v179
	s_nop 0
	s_lshr_b32 s32, s32, 8
	s_cmp_eq_u32 s32, 0
	s_cselect_b64 vcc, -1, 0
.LBB0_896:
	ds_read_b128 v[130:133], v230
	ds_read_b128 v[134:137], v230 offset:1024
	ds_read_b128 v[138:141], v230 offset:2048
	ds_read_b128 v[142:145], v230 offset:3072
	ds_read_b128 v[146:149], v231
	ds_read_b128 v[150:153], v231 offset:1024
	ds_read_b128 v[154:157], v231 offset:2048
	ds_read_b128 v[158:161], v231 offset:3072
	s_add_u32 s34, s10, 0xfff80080
	s_addc_u32 s35, s11, -1
	s_cmp_eq_u32 s73, 28
	s_cselect_b32 s77, s1, s35
	s_cselect_b32 s76, s9, s34
	s_cselect_b32 s75, s41, s72
	s_cselect_b32 s74, s65, s67
	v_lshl_add_u64 v[120:121], s[10:11], 0, v[170:171]
	s_add_i32 m0, s90, 0xc000
	ds_read_b128 v[182:185], v232
	ds_read_b128 v[186:189], v232 offset:1024
	ds_read_b128 v[190:193], v232 offset:2048
	ds_read_b128 v[194:197], v232 offset:3072
	ds_read_b128 v[198:201], v232 offset:4096
	ds_read_b128 v[202:205], v232 offset:5120
	ds_read_b128 v[206:209], v232 offset:6144
	ds_read_b128 v[210:213], v232 offset:7168
	global_load_lds_dwordx4 v[120:121], off
	v_lshl_add_u64 v[120:121], s[10:11], 0, v[172:173]
	s_add_i32 m0, s90, 0xe000
	s_nop 0
	global_load_lds_dwordx4 v[120:121], off
	s_cbranch_vccnz .Lkw_skip_896_0
	s_waitcnt vmcnt(8)
.Lkw_skip_896_0:
	s_waitcnt lgkmcnt(0)
	s_barrier
	s_setprio 1
	s_waitcnt lgkmcnt(0)
	v_mfma_f32_16x16x32_bf16 v[126:129], v[130:133], v[182:185], v[126:129]
	v_mfma_f32_16x16x32_bf16 v[92:95], v[138:141], v[182:185], v[92:95]
	v_mfma_f32_16x16x32_bf16 v[108:111], v[130:133], v[190:193], v[108:111]
	v_mfma_f32_16x16x32_bf16 v[68:71], v[138:141], v[190:193], v[68:71]
	v_mfma_f32_16x16x32_bf16 v[100:103], v[130:133], v[198:201], v[100:103]
	v_mfma_f32_16x16x32_bf16 v[64:67], v[138:141], v[198:201], v[64:67]
	v_mfma_f32_16x16x32_bf16 v[116:119], v[130:133], v[206:209], v[116:119]
	v_mfma_f32_16x16x32_bf16 v[84:87], v[138:141], v[206:209], v[84:87]
	v_mfma_f32_16x16x32_bf16 v[126:129], v[134:137], v[186:189], v[126:129]
	v_mfma_f32_16x16x32_bf16 v[92:95], v[142:145], v[186:189], v[92:95]
	v_mfma_f32_16x16x32_bf16 v[108:111], v[134:137], v[194:197], v[108:111]
	v_mfma_f32_16x16x32_bf16 v[68:71], v[142:145], v[194:197], v[68:71]
	v_mfma_f32_16x16x32_bf16 v[100:103], v[134:137], v[202:205], v[100:103]
	v_mfma_f32_16x16x32_bf16 v[64:67], v[142:145], v[202:205], v[64:67]
	v_mfma_f32_16x16x32_bf16 v[116:119], v[134:137], v[210:213], v[116:119]
	v_mfma_f32_16x16x32_bf16 v[84:87], v[142:145], v[210:213], v[84:87]
	s_setprio 0
	s_setprio 1
	v_mfma_f32_16x16x32_bf16 v[120:123], v[146:149], v[182:185], v[122:125]
	v_mfma_f32_16x16x32_bf16 v[88:91], v[154:157], v[182:185], v[88:91]
	v_mfma_f32_16x16x32_bf16 v[104:107], v[146:149], v[190:193], v[104:107]
	v_mfma_f32_16x16x32_bf16 v[60:63], v[154:157], v[190:193], v[60:63]
	v_mfma_f32_16x16x32_bf16 v[96:99], v[146:149], v[198:201], v[96:99]
	v_mfma_f32_16x16x32_bf16 v[56:59], v[154:157], v[198:201], v[56:59]
	v_mfma_f32_16x16x32_bf16 v[112:115], v[146:149], v[206:209], v[112:115]
	v_mfma_f32_16x16x32_bf16 v[80:83], v[154:157], v[206:209], v[80:83]
	v_mfma_f32_16x16x32_bf16 v[120:123], v[150:153], v[186:189], v[120:123]
	v_mfma_f32_16x16x32_bf16 v[88:91], v[158:161], v[186:189], v[88:91]
	v_mfma_f32_16x16x32_bf16 v[104:107], v[150:153], v[194:197], v[104:107]
	v_mfma_f32_16x16x32_bf16 v[60:63], v[158:161], v[194:197], v[60:63]
	v_mfma_f32_16x16x32_bf16 v[96:99], v[150:153], v[202:205], v[96:99]
	v_mfma_f32_16x16x32_bf16 v[56:59], v[158:161], v[202:205], v[56:59]
	v_mfma_f32_16x16x32_bf16 v[112:115], v[150:153], v[210:213], v[112:115]
	v_mfma_f32_16x16x32_bf16 v[80:83], v[158:161], v[210:213], v[80:83]
	s_setprio 0
	s_cbranch_vccz .Lkw_post_896_0
	s_waitcnt vmcnt(8)
.Lkw_post_896_0:
	s_barrier
	s_add_i32 s34, s37, s89
	v_lshl_add_u64 v[214:215], s[74:75], 0, v[164:165]
	s_mov_b32 m0, s34
	ds_read_b128 v[182:185], v232 offset:16384
	ds_read_b128 v[186:189], v232 offset:17408
	ds_read_b128 v[190:193], v232 offset:18432
	ds_read_b128 v[194:197], v232 offset:19456
	ds_read_b128 v[198:201], v232 offset:20480
	ds_read_b128 v[202:205], v232 offset:21504
	ds_read_b128 v[206:209], v232 offset:22528
	ds_read_b128 v[210:213], v232 offset:23552
	global_load_lds_dwordx4 v[214:215], off
	s_add_i32 m0, s34, 0x2000
	s_add_u32 s34, s74, 0x80000
	v_lshl_add_u64 v[216:217], s[74:75], 0, v[168:169]
	s_addc_u32 s35, s75, 0
	s_add_i32 s78, s38, s89
	global_load_lds_dwordx4 v[216:217], off
	v_lshl_add_u64 v[124:125], s[34:35], 0, v[164:165]
	s_mov_b32 m0, s78
	v_lshl_add_u64 v[218:219], s[76:77], 0, v[162:163]
	global_load_lds_dwordx4 v[124:125], off
	v_lshl_add_u64 v[124:125], s[34:35], 0, v[168:169]
	s_add_i32 m0, s78, 0x2000
	v_lshl_add_u64 v[234:235], s[76:77], 0, v[166:167]
	global_load_lds_dwordx4 v[124:125], off
	s_mov_b32 m0, s90
	s_nop 0
	global_load_lds_dwordx4 v[218:219], off
	s_mov_b32 m0, s91
	s_nop 0
	global_load_lds_dwordx4 v[234:235], off
	s_cbranch_vccnz .Lkw_skip_896_1
	s_waitcnt vmcnt(8)
.Lkw_skip_896_1:
	s_waitcnt lgkmcnt(0)
	s_barrier
	s_setprio 1
	s_waitcnt lgkmcnt(0)
	v_mfma_f32_16x16x32_bf16 v[52:55], v[130:133], v[182:185], v[52:55]
	v_mfma_f32_16x16x32_bf16 v[20:23], v[138:141], v[182:185], v[20:23]
	v_mfma_f32_16x16x32_bf16 v[44:47], v[130:133], v[190:193], v[44:47]
	v_mfma_f32_16x16x32_bf16 v[16:19], v[138:141], v[190:193], v[16:19]
	v_mfma_f32_16x16x32_bf16 v[36:39], v[130:133], v[198:201], v[36:39]
	v_mfma_f32_16x16x32_bf16 v[12:15], v[138:141], v[198:201], v[12:15]
	v_mfma_f32_16x16x32_bf16 v[76:79], v[130:133], v[206:209], v[76:79]
	v_mfma_f32_16x16x32_bf16 v[28:31], v[138:141], v[206:209], v[28:31]
	v_mfma_f32_16x16x32_bf16 v[52:55], v[134:137], v[186:189], v[52:55]
	v_mfma_f32_16x16x32_bf16 v[20:23], v[142:145], v[186:189], v[20:23]
	v_mfma_f32_16x16x32_bf16 v[44:47], v[134:137], v[194:197], v[44:47]
	v_mfma_f32_16x16x32_bf16 v[16:19], v[142:145], v[194:197], v[16:19]
	v_mfma_f32_16x16x32_bf16 v[36:39], v[134:137], v[202:205], v[36:39]
	v_mfma_f32_16x16x32_bf16 v[12:15], v[142:145], v[202:205], v[12:15]
	v_mfma_f32_16x16x32_bf16 v[76:79], v[134:137], v[210:213], v[76:79]
	v_mfma_f32_16x16x32_bf16 v[28:31], v[142:145], v[210:213], v[28:31]
	s_setprio 0
	s_setprio 1
	v_mfma_f32_16x16x32_bf16 v[48:51], v[146:149], v[182:185], v[48:51]
	v_mfma_f32_16x16x32_bf16 v[8:11], v[154:157], v[182:185], v[8:11]
	v_mfma_f32_16x16x32_bf16 v[40:43], v[146:149], v[190:193], v[40:43]
	v_mfma_f32_16x16x32_bf16 v[4:7], v[154:157], v[190:193], v[4:7]
	v_mfma_f32_16x16x32_bf16 v[32:35], v[146:149], v[198:201], v[32:35]
	v_mfma_f32_16x16x32_bf16 v[0:3], v[154:157], v[198:201], v[0:3]
	v_mfma_f32_16x16x32_bf16 v[72:75], v[146:149], v[206:209], v[72:75]
	v_mfma_f32_16x16x32_bf16 v[24:27], v[154:157], v[206:209], v[24:27]
	v_mfma_f32_16x16x32_bf16 v[48:51], v[150:153], v[186:189], v[48:51]
	v_mfma_f32_16x16x32_bf16 v[8:11], v[158:161], v[186:189], v[8:11]
	v_mfma_f32_16x16x32_bf16 v[40:43], v[150:153], v[194:197], v[40:43]
	v_mfma_f32_16x16x32_bf16 v[4:7], v[158:161], v[194:197], v[4:7]
	v_mfma_f32_16x16x32_bf16 v[32:35], v[150:153], v[202:205], v[32:35]
	v_mfma_f32_16x16x32_bf16 v[0:3], v[158:161], v[202:205], v[0:3]
	v_mfma_f32_16x16x32_bf16 v[72:75], v[150:153], v[210:213], v[72:75]
	v_mfma_f32_16x16x32_bf16 v[24:27], v[158:161], v[210:213], v[24:27]
	s_setprio 0
	s_cbranch_vccz .Lkw_post_896_1
	s_waitcnt vmcnt(8)
.Lkw_post_896_1:
	s_barrier
	s_add_i32 s78, 0, 0x18000
	v_add_u32_e32 v124, s78, v223
	s_add_i32 s79, 0, 0x1c000
	ds_read_b128 v[130:133], v124
	ds_read_b128 v[134:137], v124 offset:1024
	ds_read_b128 v[138:141], v124 offset:2048
	ds_read_b128 v[142:145], v124 offset:3072
	v_add_u32_e32 v124, s79, v223
	ds_read_b128 v[146:149], v124
	ds_read_b128 v[150:153], v124 offset:1024
	ds_read_b128 v[154:157], v124 offset:2048
	ds_read_b128 v[158:161], v124 offset:3072
	s_add_u32 s34, s76, 0x80000
	s_addc_u32 s35, s77, 0
	s_mov_b32 m0, s92
	v_lshl_add_u64 v[124:125], s[34:35], 0, v[162:163]
	ds_read_b128 v[182:185], v232 offset:32768
	ds_read_b128 v[186:189], v232 offset:33792
	ds_read_b128 v[190:193], v232 offset:34816
	ds_read_b128 v[194:197], v232 offset:35840
	ds_read_b128 v[198:201], v232 offset:36864
	ds_read_b128 v[202:205], v232 offset:37888
	ds_read_b128 v[206:209], v232 offset:38912
	ds_read_b128 v[210:213], v232 offset:39936
	global_load_lds_dwordx4 v[124:125], off
	v_lshl_add_u64 v[124:125], s[34:35], 0, v[166:167]
	s_mov_b32 m0, s93
	s_nop 0
	global_load_lds_dwordx4 v[124:125], off
	s_cbranch_vccnz .Lkw_skip_896_2
	s_waitcnt vmcnt(8)
.Lkw_skip_896_2:
	s_waitcnt lgkmcnt(0)
	s_barrier
	s_setprio 1
	s_waitcnt lgkmcnt(0)
	v_mfma_f32_16x16x32_bf16 v[124:127], v[130:133], v[182:185], v[126:129]
	v_mfma_f32_16x16x32_bf16 v[92:95], v[138:141], v[182:185], v[92:95]
	v_mfma_f32_16x16x32_bf16 v[108:111], v[130:133], v[190:193], v[108:111]
	v_mfma_f32_16x16x32_bf16 v[68:71], v[138:141], v[190:193], v[68:71]
	v_mfma_f32_16x16x32_bf16 v[100:103], v[130:133], v[198:201], v[100:103]
	v_mfma_f32_16x16x32_bf16 v[64:67], v[138:141], v[198:201], v[64:67]
	v_mfma_f32_16x16x32_bf16 v[116:119], v[130:133], v[206:209], v[116:119]
	v_mfma_f32_16x16x32_bf16 v[84:87], v[138:141], v[206:209], v[84:87]
	v_mfma_f32_16x16x32_bf16 v[126:129], v[134:137], v[186:189], v[124:127]
	v_mfma_f32_16x16x32_bf16 v[92:95], v[142:145], v[186:189], v[92:95]
	v_mfma_f32_16x16x32_bf16 v[108:111], v[134:137], v[194:197], v[108:111]
	v_mfma_f32_16x16x32_bf16 v[68:71], v[142:145], v[194:197], v[68:71]
	v_mfma_f32_16x16x32_bf16 v[100:103], v[134:137], v[202:205], v[100:103]
	v_mfma_f32_16x16x32_bf16 v[64:67], v[142:145], v[202:205], v[64:67]
	v_mfma_f32_16x16x32_bf16 v[116:119], v[134:137], v[210:213], v[116:119]
	v_mfma_f32_16x16x32_bf16 v[84:87], v[142:145], v[210:213], v[84:87]
	s_setprio 0
	s_setprio 1
	v_mfma_f32_16x16x32_bf16 v[120:123], v[146:149], v[182:185], v[120:123]
	v_mfma_f32_16x16x32_bf16 v[88:91], v[154:157], v[182:185], v[88:91]
	v_mfma_f32_16x16x32_bf16 v[104:107], v[146:149], v[190:193], v[104:107]
	v_mfma_f32_16x16x32_bf16 v[60:63], v[154:157], v[190:193], v[60:63]
	v_mfma_f32_16x16x32_bf16 v[96:99], v[146:149], v[198:201], v[96:99]
	v_mfma_f32_16x16x32_bf16 v[56:59], v[154:157], v[198:201], v[56:59]
	v_mfma_f32_16x16x32_bf16 v[112:115], v[146:149], v[206:209], v[112:115]
	v_mfma_f32_16x16x32_bf16 v[80:83], v[154:157], v[206:209], v[80:83]
	v_mfma_f32_16x16x32_bf16 v[122:125], v[150:153], v[186:189], v[120:123]
	v_mfma_f32_16x16x32_bf16 v[88:91], v[158:161], v[186:189], v[88:91]
	v_mfma_f32_16x16x32_bf16 v[104:107], v[150:153], v[194:197], v[104:107]
	v_mfma_f32_16x16x32_bf16 v[60:63], v[158:161], v[194:197], v[60:63]
	v_mfma_f32_16x16x32_bf16 v[96:99], v[150:153], v[202:205], v[96:99]
	v_mfma_f32_16x16x32_bf16 v[56:59], v[158:161], v[202:205], v[56:59]
	v_mfma_f32_16x16x32_bf16 v[112:115], v[150:153], v[210:213], v[112:115]
	v_mfma_f32_16x16x32_bf16 v[80:83], v[158:161], v[210:213], v[80:83]
	s_setprio 0
	s_cbranch_vccz .Lkw_post_896_2
	s_waitcnt vmcnt(8)
.Lkw_post_896_2:
	s_barrier
	s_add_i32 s34, s78, s89
	v_lshl_add_u64 v[120:121], v[214:215], 0, s[50:51]
	s_mov_b32 m0, s34
	ds_read_b128 v[182:185], v232 offset:49152
	ds_read_b128 v[186:189], v232 offset:50176
	ds_read_b128 v[190:193], v232 offset:51200
	ds_read_b128 v[194:197], v232 offset:52224
	ds_read_b128 v[198:201], v232 offset:53248
	ds_read_b128 v[202:205], v232 offset:54272
	ds_read_b128 v[206:209], v232 offset:55296
	ds_read_b128 v[210:213], v232 offset:56320
	global_load_lds_dwordx4 v[120:121], off
	s_add_i32 m0, s34, 0x2000
	s_add_u32 s34, s74, 0x80080
	v_lshl_add_u64 v[120:121], v[216:217], 0, s[50:51]
	s_addc_u32 s35, s75, 0
	s_add_i32 s74, s79, s89
	global_load_lds_dwordx4 v[120:121], off
	v_lshl_add_u64 v[120:121], s[34:35], 0, v[164:165]
	s_mov_b32 m0, s74
	s_nop 0
	global_load_lds_dwordx4 v[120:121], off
	v_lshl_add_u64 v[120:121], s[34:35], 0, v[168:169]
	s_add_i32 m0, s74, 0x2000
	s_nop 0
	global_load_lds_dwordx4 v[120:121], off
	v_lshl_add_u64 v[120:121], v[218:219], 0, s[50:51]
	s_mov_b32 m0, s95
	s_nop 0
	global_load_lds_dwordx4 v[120:121], off
	v_lshl_add_u64 v[120:121], v[234:235], 0, s[50:51]
	s_mov_b32 m0, s96
	s_nop 0
	global_load_lds_dwordx4 v[120:121], off
	s_cbranch_vccnz .Lkw_skip_896_3
	s_waitcnt vmcnt(8)

; #define PG8_BAR __builtin_amdgcn_s_barrier()
; template <class Epi>
; __device__ __forceinline__ void gemm_phase(LAS unsigned char* lds, const Gemm g, const StaticOrder& S, const Epi& E) {
;     ...
;     for (;;) {
;         if constexpr (Epi::NPART == 2) {
;             const char* mA = cA + (size_t)K * 2; const char* mB = cB + (size_t)K * 2;
;             PG8_KLOOP(cA, cB, mA, mB)
;             E.mid(acc, cur, wr, wc, fr, fq);
;             cA = mA; cB = mB;
;         }
;         const bool has_next = S.next(ui + 1, nxt);
;         const char* nA = has_next ? (const char*)g.A + (size_t)nxt.pm * tstepA : cA; const char* nB = has_next ? (const char*)g.Bt + (size_t)nxt.pn * tstepB : cB;
;         PG8_KLOOP(cA, cB, nA, nB)
;         if (wr == 0) PG8_BAR;
.Lkw_post_896_3:
	s_barrier
	s_add_i32 s73, s73, 2
	s_add_u32 s10, s10, 0x100
	s_addc_u32 s11, s11, 0
	s_add_u32 s67, s67, 0x100
	s_addc_u32 s72, s72, 0
	s_cmp_gt_u32 s73, 29
	s_cbranch_scc0 .LBB0_896
	s_and_b64 vcc, exec, s[52:53]
	s_cbranch_vccz .LBB0_899
	s_barrier

; template <class Epi>
; __device__ __forceinline__ void gemm_phase(LAS unsigned char* lds, const Gemm g, const StaticOrder& S, const Epi& E) {
;     ...
;         for (int a = 0; a < 2; ++a)
; #pragma unroll
;             for (int b = 0; b < 2; ++b)
; #pragma unroll
;                 for (int m = 0; m < 4; ++m)
; #pragma unroll
;                     for (int n = 0; n < 2; ++n) acc[a][b][m][n] = (f32x4){0.f, 0.f, 0.f, 0.f};
;         cur = nxt; cA = nA; cB = nB; ++ui;
.LBB0_1127:
	s_add_u32 s26, s26, 0x160080
	s_addc_u32 s27, s27, 0
	s_add_u32 s54, s38, 0x100
	v_mov_b32_e32 v0, 0
	s_addc_u32 s55, s39, 0
	s_mov_b32 s56, -2
	v_mov_b32_e32 v1, v0
	v_mov_b32_e32 v2, v0
	v_mov_b32_e32 v3, v0
	v_mov_b32_e32 v4, v0
	v_mov_b32_e32 v5, v0
	v_mov_b32_e32 v6, v0
	v_mov_b32_e32 v7, v0
	v_mov_b32_e32 v8, v0
	v_mov_b32_e32 v9, v0
	v_mov_b32_e32 v10, v0
	v_mov_b32_e32 v11, v0
	v_mov_b32_e32 v16, v0
	v_mov_b32_e32 v17, v0
	v_mov_b32_e32 v18, v0
	v_mov_b32_e32 v19, v0
	v_mov_b32_e32 v24, v0
	v_mov_b32_e32 v25, v0
	v_mov_b32_e32 v26, v0
	v_mov_b32_e32 v27, v0
	v_mov_b32_e32 v32, v0
	v_mov_b32_e32 v33, v0
	v_mov_b32_e32 v34, v0
	v_mov_b32_e32 v35, v0
	v_mov_b32_e32 v44, v0
	v_mov_b32_e32 v45, v0
	v_mov_b32_e32 v46, v0
	v_mov_b32_e32 v47, v0
	v_mov_b32_e32 v52, v0
	v_mov_b32_e32 v53, v0
	v_mov_b32_e32 v54, v0
	v_mov_b32_e32 v55, v0
	v_mov_b32_e32 v12, v0
	v_mov_b32_e32 v13, v0
	v_mov_b32_e32 v14, v0
	v_mov_b32_e32 v15, v0
	v_mov_b32_e32 v20, v0
	v_mov_b32_e32 v21, v0
	v_mov_b32_e32 v22, v0
	v_mov_b32_e32 v23, v0
	v_mov_b32_e32 v28, v0
	v_mov_b32_e32 v29, v0
	v_mov_b32_e32 v30, v0
	v_mov_b32_e32 v31, v0
	v_mov_b32_e32 v36, v0
	v_mov_b32_e32 v37, v0
	v_mov_b32_e32 v38, v0
	v_mov_b32_e32 v39, v0
	v_mov_b32_e32 v40, v0
	v_mov_b32_e32 v41, v0
	v_mov_b32_e32 v42, v0
	v_mov_b32_e32 v43, v0
	v_mov_b32_e32 v48, v0
	v_mov_b32_e32 v49, v0
	v_mov_b32_e32 v50, v0
	v_mov_b32_e32 v51, v0
	v_mov_b32_e32 v56, v0
	v_mov_b32_e32 v57, v0
	v_mov_b32_e32 v58, v0
	v_mov_b32_e32 v59, v0
	v_mov_b32_e32 v60, v0
	v_mov_b32_e32 v61, v0
	v_mov_b32_e32 v62, v0
	v_mov_b32_e32 v63, v0
	v_mov_b32_e32 v80, v0
	v_mov_b32_e32 v81, v0
	v_mov_b32_e32 v82, v0
	v_mov_b32_e32 v83, v0
	v_mov_b32_e32 v84, v0
	v_mov_b32_e32 v85, v0
	v_mov_b32_e32 v86, v0
	v_mov_b32_e32 v87, v0
	v_mov_b32_e32 v88, v0
	v_mov_b32_e32 v89, v0
	v_mov_b32_e32 v90, v0
	v_mov_b32_e32 v91, v0
	v_mov_b32_e32 v100, v0
	v_mov_b32_e32 v101, v0
	v_mov_b32_e32 v102, v0
	v_mov_b32_e32 v103, v0
	v_mov_b32_e32 v104, v0
	v_mov_b32_e32 v105, v0
	v_mov_b32_e32 v106, v0
	v_mov_b32_e32 v107, v0
	v_mov_b32_e32 v108, v0
	v_mov_b32_e32 v109, v0
	v_mov_b32_e32 v110, v0
	v_mov_b32_e32 v111, v0
	v_mov_b32_e32 v64, v0
	v_mov_b32_e32 v65, v0
	v_mov_b32_e32 v66, v0
	v_mov_b32_e32 v67, v0
	v_mov_b32_e32 v68, v0
	v_mov_b32_e32 v69, v0
	v_mov_b32_e32 v70, v0
	v_mov_b32_e32 v71, v0
	v_mov_b32_e32 v92, v0
	v_mov_b32_e32 v93, v0
	v_mov_b32_e32 v94, v0
	v_mov_b32_e32 v95, v0
	v_mov_b32_e32 v96, v0
	v_mov_b32_e32 v97, v0
	v_mov_b32_e32 v98, v0
	v_mov_b32_e32 v99, v0
	v_mov_b32_e32 v112, v0
	v_mov_b32_e32 v113, v0
	v_mov_b32_e32 v114, v0
	v_mov_b32_e32 v115, v0
	v_mov_b32_e32 v116, v0
	v_mov_b32_e32 v117, v0
	v_mov_b32_e32 v118, v0
	v_mov_b32_e32 v119, v0
	v_mov_b32_e32 v120, v0
	v_mov_b32_e32 v121, v0
	v_mov_b32_e32 v122, v0
	v_mov_b32_e32 v123, v0
	v_mov_b32_e32 v124, v0
	v_mov_b32_e32 v125, v0
	v_mov_b32_e32 v126, v0
	v_mov_b32_e32 v127, v0
	v_mov_b32_e32 v72, v0
	v_mov_b32_e32 v73, v0
	v_mov_b32_e32 v74, v0
	v_mov_b32_e32 v75, v0
	v_mov_b32_e32 v76, v0
	v_mov_b32_e32 v77, v0
	v_mov_b32_e32 v78, v0
	v_mov_b32_e32 v79, v0
	v_readfirstlane_b32 s32, v179
	s_nop 0
	s_lshr_b32 s32, s32, 8
	s_cmp_eq_u32 s32, 0
	s_cselect_b64 vcc, -1, 0
.LBB0_1128:
	ds_read_b128 v[128:131], v158
	ds_read_b128 v[132:135], v158 offset:1024
	ds_read_b128 v[146:149], v158 offset:2048
	ds_read_b128 v[162:165], v158 offset:3072
	ds_read_b128 v[166:169], v159
	ds_read_b128 v[170:173], v159 offset:1024
	ds_read_b128 v[180:183], v159 offset:2048
	ds_read_b128 v[184:187], v159 offset:3072
	s_add_u32 s34, s26, 0xffea0080
	s_addc_u32 s35, s27, -1
	s_cmpk_eq_i32 s56, 0x54
	s_cselect_b32 s43, s1, s35
	s_cselect_b32 s42, s0, s34
	s_cselect_b32 s39, s25, s55
	s_cselect_b32 s38, s24, s54
	v_lshl_add_u64 v[150:151], s[26:27], 0, v[136:137]
	s_add_i32 m0, s40, 0xc000
	ds_read_b128 v[188:191], v160
	ds_read_b128 v[192:195], v160 offset:1024
	ds_read_b128 v[196:199], v160 offset:2048
	ds_read_b128 v[200:203], v160 offset:3072
	ds_read_b128 v[204:207], v160 offset:4096
	ds_read_b128 v[208:211], v160 offset:5120
	ds_read_b128 v[212:215], v160 offset:6144
	ds_read_b128 v[216:219], v160 offset:7168
	global_load_lds_dwordx4 v[150:151], off
	v_lshl_add_u64 v[150:151], s[26:27], 0, v[140:141]
	s_add_i32 m0, s40, 0xe000
	s_nop 0
	global_load_lds_dwordx4 v[150:151], off
	s_cbranch_vccnz .Lkw_skip_1128_0
	s_waitcnt vmcnt(8)
.Lkw_skip_1128_0:
	s_waitcnt lgkmcnt(0)
	s_barrier
	s_setprio 1
	s_waitcnt lgkmcnt(0)
	v_mfma_f32_16x16x32_bf16 v[76:79], v[128:131], v[188:191], v[76:79]
	v_mfma_f32_16x16x32_bf16 v[72:75], v[146:149], v[188:191], v[72:75]
	v_mfma_f32_16x16x32_bf16 v[124:127], v[128:131], v[196:199], v[124:127]
	v_mfma_f32_16x16x32_bf16 v[120:123], v[146:149], v[196:199], v[120:123]
	v_mfma_f32_16x16x32_bf16 v[116:119], v[128:131], v[204:207], v[116:119]
	v_mfma_f32_16x16x32_bf16 v[112:115], v[146:149], v[204:207], v[112:115]
	v_mfma_f32_16x16x32_bf16 v[96:99], v[128:131], v[212:215], v[96:99]
	v_mfma_f32_16x16x32_bf16 v[92:95], v[146:149], v[212:215], v[92:95]
	v_mfma_f32_16x16x32_bf16 v[76:79], v[132:135], v[192:195], v[76:79]
	v_mfma_f32_16x16x32_bf16 v[72:75], v[162:165], v[192:195], v[72:75]
	v_mfma_f32_16x16x32_bf16 v[124:127], v[132:135], v[200:203], v[124:127]
	v_mfma_f32_16x16x32_bf16 v[120:123], v[162:165], v[200:203], v[120:123]
	v_mfma_f32_16x16x32_bf16 v[116:119], v[132:135], v[208:211], v[116:119]
	v_mfma_f32_16x16x32_bf16 v[112:115], v[162:165], v[208:211], v[112:115]
	v_mfma_f32_16x16x32_bf16 v[96:99], v[132:135], v[216:219], v[96:99]
	v_mfma_f32_16x16x32_bf16 v[92:95], v[162:165], v[216:219], v[92:95]
	s_setprio 0
	s_setprio 1
	v_mfma_f32_16x16x32_bf16 v[68:71], v[166:169], v[188:191], v[68:71]
	v_mfma_f32_16x16x32_bf16 v[64:67], v[180:183], v[188:191], v[64:67]
	v_mfma_f32_16x16x32_bf16 v[108:111], v[166:169], v[196:199], v[108:111]
	v_mfma_f32_16x16x32_bf16 v[104:107], v[180:183], v[196:199], v[104:107]
	v_mfma_f32_16x16x32_bf16 v[100:103], v[166:169], v[204:207], v[100:103]
	v_mfma_f32_16x16x32_bf16 v[88:91], v[180:183], v[204:207], v[88:91]
	v_mfma_f32_16x16x32_bf16 v[84:87], v[166:169], v[212:215], v[84:87]
	v_mfma_f32_16x16x32_bf16 v[80:83], v[180:183], v[212:215], v[80:83]
	v_mfma_f32_16x16x32_bf16 v[68:71], v[170:173], v[192:195], v[68:71]
	v_mfma_f32_16x16x32_bf16 v[64:67], v[184:187], v[192:195], v[64:67]
	v_mfma_f32_16x16x32_bf16 v[108:111], v[170:173], v[200:203], v[108:111]
	v_mfma_f32_16x16x32_bf16 v[104:107], v[184:187], v[200:203], v[104:107]
	v_mfma_f32_16x16x32_bf16 v[100:103], v[170:173], v[208:211], v[100:103]
	v_mfma_f32_16x16x32_bf16 v[88:91], v[184:187], v[208:211], v[88:91]
	v_mfma_f32_16x16x32_bf16 v[84:87], v[170:173], v[216:219], v[84:87]
	v_mfma_f32_16x16x32_bf16 v[80:83], v[184:187], v[216:219], v[80:83]
	s_setprio 0
	s_cbranch_vccz .Lkw_post_1128_0
	s_waitcnt vmcnt(8)
.Lkw_post_1128_0:
	s_barrier
	s_add_i32 s34, s8, s33
	v_lshl_add_u64 v[150:151], s[38:39], 0, v[138:139]
	s_mov_b32 m0, s34
	ds_read_b128 v[188:191], v160 offset:16384
	ds_read_b128 v[192:195], v160 offset:17408
	ds_read_b128 v[196:199], v160 offset:18432
	ds_read_b128 v[200:203], v160 offset:19456
	ds_read_b128 v[204:207], v160 offset:20480
	ds_read_b128 v[208:211], v160 offset:21504
	ds_read_b128 v[212:215], v160 offset:22528
	ds_read_b128 v[216:219], v160 offset:23552
	global_load_lds_dwordx4 v[150:151], off
	s_add_i32 m0, s34, 0x2000
	s_add_u32 s34, s38, 0x160000
	v_lshl_add_u64 v[174:175], s[38:39], 0, v[142:143]
	s_addc_u32 s35, s39, 0
	s_add_i32 s57, s49, s33
	global_load_lds_dwordx4 v[174:175], off
	v_lshl_add_u64 v[222:223], s[34:35], 0, v[138:139]
	s_mov_b32 m0, s57
	v_lshl_add_u64 v[224:225], s[42:43], 0, v[140:141]
	global_load_lds_dwordx4 v[222:223], off
	v_lshl_add_u64 v[222:223], s[34:35], 0, v[142:143]
	s_add_i32 m0, s57, 0x2000
	s_nop 0
	global_load_lds_dwordx4 v[222:223], off
	v_lshl_add_u64 v[222:223], s[42:43], 0, v[136:137]
	s_mov_b32 m0, s40
	s_nop 0
	global_load_lds_dwordx4 v[222:223], off
	s_mov_b32 m0, s41
	s_nop 0
	global_load_lds_dwordx4 v[224:225], off
	s_cbranch_vccnz .Lkw_skip_1128_1
	s_waitcnt vmcnt(8)
.Lkw_skip_1128_1:
	s_waitcnt lgkmcnt(0)
	s_barrier
	s_setprio 1
	s_waitcnt lgkmcnt(0)
	v_mfma_f32_16x16x32_bf16 v[60:63], v[128:131], v[188:191], v[60:63]
	v_mfma_f32_16x16x32_bf16 v[56:59], v[146:149], v[188:191], v[56:59]
	v_mfma_f32_16x16x32_bf16 v[48:51], v[128:131], v[196:199], v[48:51]
	v_mfma_f32_16x16x32_bf16 v[40:43], v[146:149], v[196:199], v[40:43]
	v_mfma_f32_16x16x32_bf16 v[36:39], v[128:131], v[204:207], v[36:39]
	v_mfma_f32_16x16x32_bf16 v[28:31], v[146:149], v[204:207], v[28:31]
	v_mfma_f32_16x16x32_bf16 v[20:23], v[128:131], v[212:215], v[20:23]
	v_mfma_f32_16x16x32_bf16 v[12:15], v[146:149], v[212:215], v[12:15]
	v_mfma_f32_16x16x32_bf16 v[60:63], v[132:135], v[192:195], v[60:63]
	v_mfma_f32_16x16x32_bf16 v[56:59], v[162:165], v[192:195], v[56:59]
	v_mfma_f32_16x16x32_bf16 v[48:51], v[132:135], v[200:203], v[48:51]
	v_mfma_f32_16x16x32_bf16 v[40:43], v[162:165], v[200:203], v[40:43]
	v_mfma_f32_16x16x32_bf16 v[36:39], v[132:135], v[208:211], v[36:39]
	v_mfma_f32_16x16x32_bf16 v[28:31], v[162:165], v[208:211], v[28:31]
	v_mfma_f32_16x16x32_bf16 v[20:23], v[132:135], v[216:219], v[20:23]
	v_mfma_f32_16x16x32_bf16 v[12:15], v[162:165], v[216:219], v[12:15]
	s_setprio 0
	s_setprio 1
	v_mfma_f32_16x16x32_bf16 v[52:55], v[166:169], v[188:191], v[52:55]
	v_mfma_f32_16x16x32_bf16 v[44:47], v[180:183], v[188:191], v[44:47]
	v_mfma_f32_16x16x32_bf16 v[32:35], v[166:169], v[196:199], v[32:35]
	v_mfma_f32_16x16x32_bf16 v[24:27], v[180:183], v[196:199], v[24:27]
	v_mfma_f32_16x16x32_bf16 v[16:19], v[166:169], v[204:207], v[16:19]
	v_mfma_f32_16x16x32_bf16 v[8:11], v[180:183], v[204:207], v[8:11]
	v_mfma_f32_16x16x32_bf16 v[4:7], v[166:169], v[212:215], v[4:7]
	v_mfma_f32_16x16x32_bf16 v[0:3], v[180:183], v[212:215], v[0:3]
	v_mfma_f32_16x16x32_bf16 v[52:55], v[170:173], v[192:195], v[52:55]
	v_mfma_f32_16x16x32_bf16 v[44:47], v[184:187], v[192:195], v[44:47]
	v_mfma_f32_16x16x32_bf16 v[32:35], v[170:173], v[200:203], v[32:35]
	v_mfma_f32_16x16x32_bf16 v[24:27], v[184:187], v[200:203], v[24:27]
	v_mfma_f32_16x16x32_bf16 v[16:19], v[170:173], v[208:211], v[16:19]
	v_mfma_f32_16x16x32_bf16 v[8:11], v[184:187], v[208:211], v[8:11]
	v_mfma_f32_16x16x32_bf16 v[4:7], v[170:173], v[216:219], v[4:7]
	v_mfma_f32_16x16x32_bf16 v[0:3], v[184:187], v[216:219], v[0:3]
	s_setprio 0
	s_cbranch_vccz .Lkw_post_1128_1
	s_waitcnt vmcnt(8)
.Lkw_post_1128_1:
	s_barrier
	s_add_i32 s57, 0, 0x18000
	v_add_u32_e32 v161, s57, v153
	s_add_i32 s58, 0, 0x1c000
	ds_read_b128 v[128:131], v161
	ds_read_b128 v[132:135], v161 offset:1024
	ds_read_b128 v[146:149], v161 offset:2048
	ds_read_b128 v[162:165], v161 offset:3072
	v_add_u32_e32 v161, s58, v153
	ds_read_b128 v[166:169], v161
	ds_read_b128 v[170:173], v161 offset:1024
	ds_read_b128 v[180:183], v161 offset:2048
	ds_read_b128 v[184:187], v161 offset:3072
	s_add_u32 s34, s42, 0x160000
	s_addc_u32 s35, s43, 0
	s_mov_b32 m0, s44
	v_lshl_add_u64 v[226:227], s[34:35], 0, v[136:137]
	ds_read_b128 v[188:191], v160 offset:32768
	ds_read_b128 v[192:195], v160 offset:33792
	ds_read_b128 v[196:199], v160 offset:34816
	ds_read_b128 v[200:203], v160 offset:35840
	ds_read_b128 v[204:207], v160 offset:36864
	ds_read_b128 v[208:211], v160 offset:37888
	ds_read_b128 v[212:215], v160 offset:38912
	ds_read_b128 v[216:219], v160 offset:39936
	global_load_lds_dwordx4 v[226:227], off
	v_lshl_add_u64 v[226:227], s[34:35], 0, v[140:141]
	s_mov_b32 m0, s45
	s_nop 0
	global_load_lds_dwordx4 v[226:227], off
	s_cbranch_vccnz .Lkw_skip_1128_2
	s_waitcnt vmcnt(8)

.Lkw_post_1128_2:
	s_barrier
	s_add_i32 s34, s57, s33
	v_lshl_add_u64 v[150:151], v[150:151], 0, s[14:15]
	s_mov_b32 m0, s34
	ds_read_b128 v[188:191], v160 offset:49152
	ds_read_b128 v[192:195], v160 offset:50176
	ds_read_b128 v[196:199], v160 offset:51200
	ds_read_b128 v[200:203], v160 offset:52224
	ds_read_b128 v[204:207], v160 offset:53248
	ds_read_b128 v[208:211], v160 offset:54272
	ds_read_b128 v[212:215], v160 offset:55296
	ds_read_b128 v[216:219], v160 offset:56320
	global_load_lds_dwordx4 v[150:151], off
	s_add_i32 m0, s34, 0x2000
	s_add_u32 s34, s38, 0x160080
	v_lshl_add_u64 v[150:151], v[174:175], 0, s[14:15]
	s_addc_u32 s35, s39, 0
	s_add_i32 s38, s58, s33
	global_load_lds_dwordx4 v[150:151], off
	v_lshl_add_u64 v[150:151], s[34:35], 0, v[138:139]
	s_mov_b32 m0, s38
	s_nop 0
	global_load_lds_dwordx4 v[150:151], off
	v_lshl_add_u64 v[150:151], s[34:35], 0, v[142:143]
	s_add_i32 m0, s38, 0x2000
	s_nop 0
	global_load_lds_dwordx4 v[150:151], off
	v_lshl_add_u64 v[150:151], v[222:223], 0, s[14:15]
	s_mov_b32 m0, s46
	s_nop 0
	global_load_lds_dwordx4 v[150:151], off
	v_lshl_add_u64 v[150:151], v[224:225], 0, s[14:15]
	s_mov_b32 m0, s47
	s_nop 0
	global_load_lds_dwordx4 v[150:151], off
	s_cbranch_vccnz .Lkw_skip_1128_3
	s_waitcnt vmcnt(8)

; #define PG8_BAR __builtin_amdgcn_s_barrier()
; template <class Epi>
; __device__ __forceinline__ void gemm_phase(LAS unsigned char* lds, const Gemm g, const StaticOrder& S, const Epi& E) {
;     ...
;     for (;;) {
;         if constexpr (Epi::NPART == 2) {
;             const char* mA = cA + (size_t)K * 2; const char* mB = cB + (size_t)K * 2;
;             PG8_KLOOP(cA, cB, mA, mB)
;             E.mid(acc, cur, wr, wc, fr, fq);
;             cA = mA; cB = mB;
;         }
;         const bool has_next = S.next(ui + 1, nxt);
;         const char* nA = has_next ? (const char*)g.A + (size_t)nxt.pm * tstepA : cA; const char* nB = has_next ? (const char*)g.Bt + (size_t)nxt.pn * tstepB : cB;
;         PG8_KLOOP(cA, cB, nA, nB)
;         if (wr == 0) PG8_BAR;
.Lkw_post_1128_3:
	s_barrier
	s_add_i32 s56, s56, 2
	s_add_u32 s26, s26, 0x100
	s_addc_u32 s27, s27, 0
	s_add_u32 s54, s54, 0x100
	s_addc_u32 s55, s55, 0
	s_cmpk_gt_u32 s56, 0x55
	s_cbranch_scc0 .LBB0_1128
	s_and_b64 vcc, exec, s[22:23]
	s_cbranch_vccz .LBB0_1131
	s_barrier
